# GEMM_IN epilogue: adjacent column tiles exchanged with v_permlane16_swap so every lane stores 16 contiguous bytes (64 B per row per store)
# speedup vs baseline: 1.0303x; 1.0209x over previous
.LBB0_271:
	v_and_b32_e32 v150, 63, v128
	v_lshrrev_b32_e32 v151, 6, v128
	v_lshrrev_b32_e32 v152, 3, v150
	v_readfirstlane_b32 s0, v151
	v_and_b32_e32 v153, 7, v150
	v_xor_b32_e32 v153, v153, v152
	v_lshlrev_b32_e32 v153, 4, v153
	v_lshl_add_u32 v153, v152, 11, v153
	s_lshl_b32 s1, s0, 16
	v_add_u32_e32 v132, s1, v153
	v_add_u32_e32 v133, 0x3c00, v132
	v_add_u32_e32 v134, 0x7800, v132
	v_add_u32_e32 v135, 0xb400, v132
	s_lshl_b32 s1, s0, 12
	s_add_u32 s5, s1, 0
	s_add_u32 s6, s1, 16384
	s_add_u32 s7, s1, 45056
	s_add_u32 s8, s1, 61440
	v_and_b32_e32 v152, 15, v150
	v_lshrrev_b32_e32 v153, 4, v150
	v_and_b32_e32 v154, 7, v152
	v_xor_b32_e32 v154, v154, v153
	v_lshlrev_b32_e32 v154, 4, v154
	v_lshl_add_u32 v154, v152, 7, v154
	s_lshr_b32 s1, s0, 1
	s_lshl_b32 s1, s1, 13
	v_add_u32_e32 v136, s1, v154
	v_xor_b32_e32 v137, 64, v136
	v_add_u32_e32 v138, 0xb000, v136
	v_add_u32_e32 v139, 0xb000, v137
	s_and_b32 s1, s0, 1
	s_lshl_b32 s1, s1, 13
	s_add_u32 s1, s1, 16384
	v_add_u32_e32 v140, s1, v154
	v_xor_b32_e32 v141, 64, v140
	v_add_u32_e32 v142, 0xb000, v140
	v_add_u32_e32 v143, 0xb000, v141
	s_and_b32 s1, s0, 1
	s_lshl_b32 s1, s1, 6
	v_add_u32_e32 v152, s1, v152
	v_mov_b32_e32 v154, 0x4a00
	v_mul_lo_u32 v152, v152, v154
	v_and_b32_e32 v154, 1, v153
	v_lshrrev_b32_e32 v153, 1, v153
	v_lshlrev_b32_e32 v153, 4, v153
	v_lshl_or_b32 v153, v154, 5, v153
	s_lshr_b32 s1, s0, 1
	s_lshl_b32 s1, s1, 7
	v_add3_u32 v146, v152, v153, s1
	v_add_u32_e32 v147, 0x4a000, v146
	v_add_u32_e32 v148, 0x94000, v146
	v_add_u32_e32 v149, 0xde000, v146
	v_readlane_b32 s25, v252, 0
	s_mov_b32 s101, s25
	s_mov_b32 s100, 0
	s_and_b32 s0, s25, 7
	s_lshl_b32 s0, s0, 9
	s_add_i32 s25, s25, s0
	v_readlane_b32 s98, v252, 0
	s_and_b32 s99, s98, 7
	s_lshr_b32 s98, s98, 3
	s_lshl_b32 s99, s99, 1
	s_add_i32 s98, s98, s99
	s_and_b32 s98, s98, 15
	s_and_b32 s0, s25, 63
	s_lshr_b32 s1, s25, 6
	s_mul_i32 s4, s70, 0x1280000
	s_lshl_b32 s39, s1, 18
	s_add_u32 s4, s4, s39
	s_add_u32 s26, s96, s4
	s_addc_u32 s27, s97, 0
	s_lshl_b32 s4, s0, 18
	s_add_u32 s4, s4, 0x82a6100
	s_add_u32 s28, s96, s4
	s_addc_u32 s29, s97, 0
	s_lshl_b32 s0, s98, 7
	s_add_u32 s26, s26, s0
	s_addc_u32 s27, s27, 0
	s_add_u32 s28, s28, s0
	s_addc_u32 s29, s29, 0
	s_mov_b32 s99, s98
	s_mov_b32 m0, s5
	s_nop 0
	global_load_lds_dwordx4 v132, s[26:27] offset:0
	global_load_lds_dwordx4 v133, s[26:27] offset:1024
	global_load_lds_dwordx4 v134, s[26:27] offset:2048
	global_load_lds_dwordx4 v135, s[26:27] offset:3072
	s_mov_b32 m0, s6
	s_nop 0
	global_load_lds_dwordx4 v132, s[28:29] offset:0
	global_load_lds_dwordx4 v133, s[28:29] offset:1024
	global_load_lds_dwordx4 v134, s[28:29] offset:2048
	global_load_lds_dwordx4 v135, s[28:29] offset:3072
	s_waitcnt vmcnt(0)
.Lgin_tile:
	s_waitcnt vmcnt(8)
	s_barrier
	s_add_i32 s99, s99, 1
	s_cmp_eq_u32 s99, 16
	s_movk_i32 s0, 0x80
	s_cselect_b32 s0, 0xfffff880, s0
	s_cselect_b32 s99, 0, s99
	s_ashr_i32 s1, s0, 31
	s_add_u32 s26, s26, s0
	s_addc_u32 s27, s27, s1
	s_add_u32 s28, s28, s0
	s_addc_u32 s29, s29, s1
	s_mov_b32 m0, s7
	s_nop 0
	global_load_lds_dwordx4 v132, s[26:27] offset:0
	global_load_lds_dwordx4 v133, s[26:27] offset:1024
	global_load_lds_dwordx4 v134, s[26:27] offset:2048
	global_load_lds_dwordx4 v135, s[26:27] offset:3072
	s_mov_b32 m0, s8
	s_nop 0
	global_load_lds_dwordx4 v132, s[28:29] offset:0
	global_load_lds_dwordx4 v133, s[28:29] offset:1024
	global_load_lds_dwordx4 v134, s[28:29] offset:2048
	global_load_lds_dwordx4 v135, s[28:29] offset:3072
	ds_read_b128 v[64:67], v136 offset:0
	ds_read_b128 v[96:99], v140 offset:0
	ds_read_b128 v[100:103], v140 offset:2048
	ds_read_b128 v[104:107], v140 offset:4096
	ds_read_b128 v[108:111], v140 offset:6144
	ds_read_b128 v[68:71], v136 offset:2048
	ds_read_b128 v[72:75], v136 offset:4096
	ds_read_b128 v[76:79], v136 offset:6144
	s_waitcnt lgkmcnt(3)
	v_mfma_f32_16x16x32_bf16 v[0:3], v[64:67], v[96:99], 0
	v_mfma_f32_16x16x32_bf16 v[4:7], v[64:67], v[100:103], 0
	ds_read_b128 v[80:83], v137 offset:0
	v_mfma_f32_16x16x32_bf16 v[8:11], v[64:67], v[104:107], 0
	v_mfma_f32_16x16x32_bf16 v[12:15], v[64:67], v[108:111], 0
	ds_read_b128 v[112:115], v141 offset:0
	s_waitcnt lgkmcnt(4)
	v_mfma_f32_16x16x32_bf16 v[16:19], v[68:71], v[96:99], 0
	v_mfma_f32_16x16x32_bf16 v[20:23], v[68:71], v[100:103], 0
	ds_read_b128 v[116:119], v141 offset:2048
	v_mfma_f32_16x16x32_bf16 v[24:27], v[68:71], v[104:107], 0
	v_mfma_f32_16x16x32_bf16 v[28:31], v[68:71], v[108:111], 0
	ds_read_b128 v[120:123], v141 offset:4096
	s_waitcnt lgkmcnt(5)
	v_mfma_f32_16x16x32_bf16 v[32:35], v[72:75], v[96:99], 0
	v_mfma_f32_16x16x32_bf16 v[36:39], v[72:75], v[100:103], 0
	ds_read_b128 v[124:127], v141 offset:6144
	v_mfma_f32_16x16x32_bf16 v[40:43], v[72:75], v[104:107], 0
	v_mfma_f32_16x16x32_bf16 v[44:47], v[72:75], v[108:111], 0
	ds_read_b128 v[84:87], v137 offset:2048
	s_waitcnt lgkmcnt(6)
	v_mfma_f32_16x16x32_bf16 v[48:51], v[76:79], v[96:99], 0
	v_mfma_f32_16x16x32_bf16 v[52:55], v[76:79], v[100:103], 0
	ds_read_b128 v[88:91], v137 offset:4096
	v_mfma_f32_16x16x32_bf16 v[56:59], v[76:79], v[104:107], 0
	v_mfma_f32_16x16x32_bf16 v[60:63], v[76:79], v[108:111], 0
	ds_read_b128 v[92:95], v137 offset:6144
	s_waitcnt lgkmcnt(3)
	v_mfma_f32_16x16x32_bf16 v[0:3], v[80:83], v[112:115], v[0:3]
	v_mfma_f32_16x16x32_bf16 v[4:7], v[80:83], v[116:119], v[4:7]
	v_mfma_f32_16x16x32_bf16 v[8:11], v[80:83], v[120:123], v[8:11]
	v_mfma_f32_16x16x32_bf16 v[12:15], v[80:83], v[124:127], v[12:15]
	s_waitcnt lgkmcnt(2)
	v_mfma_f32_16x16x32_bf16 v[16:19], v[84:87], v[112:115], v[16:19]
	v_mfma_f32_16x16x32_bf16 v[20:23], v[84:87], v[116:119], v[20:23]
	v_mfma_f32_16x16x32_bf16 v[24:27], v[84:87], v[120:123], v[24:27]
	v_mfma_f32_16x16x32_bf16 v[28:31], v[84:87], v[124:127], v[28:31]
	s_waitcnt lgkmcnt(1)
	v_mfma_f32_16x16x32_bf16 v[32:35], v[88:91], v[112:115], v[32:35]
	v_mfma_f32_16x16x32_bf16 v[36:39], v[88:91], v[116:119], v[36:39]
	v_mfma_f32_16x16x32_bf16 v[40:43], v[88:91], v[120:123], v[40:43]
	v_mfma_f32_16x16x32_bf16 v[44:47], v[88:91], v[124:127], v[44:47]
	s_waitcnt lgkmcnt(0)
	v_mfma_f32_16x16x32_bf16 v[48:51], v[92:95], v[112:115], v[48:51]
	v_mfma_f32_16x16x32_bf16 v[52:55], v[92:95], v[116:119], v[52:55]
	v_mfma_f32_16x16x32_bf16 v[56:59], v[92:95], v[120:123], v[56:59]
	v_mfma_f32_16x16x32_bf16 v[60:63], v[92:95], v[124:127], v[60:63]
	s_waitcnt vmcnt(0)
	s_barrier
	s_add_i32 s99, s99, 1
	s_cmp_eq_u32 s99, 16
	s_movk_i32 s0, 0x80
	s_cselect_b32 s0, 0xfffff880, s0
	s_cselect_b32 s99, 0, s99
	s_ashr_i32 s1, s0, 31
	s_add_u32 s26, s26, s0
	s_addc_u32 s27, s27, s1
	s_add_u32 s28, s28, s0
	s_addc_u32 s29, s29, s1
	s_mov_b32 m0, s5
	s_nop 0
	global_load_lds_dwordx4 v132, s[26:27] offset:0
	global_load_lds_dwordx4 v133, s[26:27] offset:1024
	global_load_lds_dwordx4 v134, s[26:27] offset:2048
	global_load_lds_dwordx4 v135, s[26:27] offset:3072
	s_mov_b32 m0, s6
	s_nop 0
	global_load_lds_dwordx4 v132, s[28:29] offset:0
	global_load_lds_dwordx4 v133, s[28:29] offset:1024
	global_load_lds_dwordx4 v134, s[28:29] offset:2048
	global_load_lds_dwordx4 v135, s[28:29] offset:3072
	ds_read_b128 v[64:67], v138 offset:0
	ds_read_b128 v[96:99], v142 offset:0
	ds_read_b128 v[100:103], v142 offset:2048
	ds_read_b128 v[104:107], v142 offset:4096
	ds_read_b128 v[108:111], v142 offset:6144
	ds_read_b128 v[68:71], v138 offset:2048
	ds_read_b128 v[72:75], v138 offset:4096
	ds_read_b128 v[76:79], v138 offset:6144
	s_waitcnt lgkmcnt(3)
	v_mfma_f32_16x16x32_bf16 v[0:3], v[64:67], v[96:99], v[0:3]
	v_mfma_f32_16x16x32_bf16 v[4:7], v[64:67], v[100:103], v[4:7]
	ds_read_b128 v[80:83], v139 offset:0
	v_mfma_f32_16x16x32_bf16 v[8:11], v[64:67], v[104:107], v[8:11]
	v_mfma_f32_16x16x32_bf16 v[12:15], v[64:67], v[108:111], v[12:15]
	ds_read_b128 v[112:115], v143 offset:0
	s_waitcnt lgkmcnt(4)
	v_mfma_f32_16x16x32_bf16 v[16:19], v[68:71], v[96:99], v[16:19]
	v_mfma_f32_16x16x32_bf16 v[20:23], v[68:71], v[100:103], v[20:23]
	ds_read_b128 v[116:119], v143 offset:2048
	v_mfma_f32_16x16x32_bf16 v[24:27], v[68:71], v[104:107], v[24:27]
	v_mfma_f32_16x16x32_bf16 v[28:31], v[68:71], v[108:111], v[28:31]
	ds_read_b128 v[120:123], v143 offset:4096
	s_waitcnt lgkmcnt(5)
	v_mfma_f32_16x16x32_bf16 v[32:35], v[72:75], v[96:99], v[32:35]
	v_mfma_f32_16x16x32_bf16 v[36:39], v[72:75], v[100:103], v[36:39]
	ds_read_b128 v[124:127], v143 offset:6144
	v_mfma_f32_16x16x32_bf16 v[40:43], v[72:75], v[104:107], v[40:43]
	v_mfma_f32_16x16x32_bf16 v[44:47], v[72:75], v[108:111], v[44:47]
	ds_read_b128 v[84:87], v139 offset:2048
	s_waitcnt lgkmcnt(6)
	v_mfma_f32_16x16x32_bf16 v[48:51], v[76:79], v[96:99], v[48:51]
	v_mfma_f32_16x16x32_bf16 v[52:55], v[76:79], v[100:103], v[52:55]
	ds_read_b128 v[88:91], v139 offset:4096
	v_mfma_f32_16x16x32_bf16 v[56:59], v[76:79], v[104:107], v[56:59]
	v_mfma_f32_16x16x32_bf16 v[60:63], v[76:79], v[108:111], v[60:63]
	ds_read_b128 v[92:95], v139 offset:6144
	s_waitcnt lgkmcnt(3)
	v_mfma_f32_16x16x32_bf16 v[0:3], v[80:83], v[112:115], v[0:3]
	v_mfma_f32_16x16x32_bf16 v[4:7], v[80:83], v[116:119], v[4:7]
	v_mfma_f32_16x16x32_bf16 v[8:11], v[80:83], v[120:123], v[8:11]
	v_mfma_f32_16x16x32_bf16 v[12:15], v[80:83], v[124:127], v[12:15]
	s_waitcnt lgkmcnt(2)
	v_mfma_f32_16x16x32_bf16 v[16:19], v[84:87], v[112:115], v[16:19]
	v_mfma_f32_16x16x32_bf16 v[20:23], v[84:87], v[116:119], v[20:23]
	v_mfma_f32_16x16x32_bf16 v[24:27], v[84:87], v[120:123], v[24:27]
	v_mfma_f32_16x16x32_bf16 v[28:31], v[84:87], v[124:127], v[28:31]
	s_waitcnt lgkmcnt(1)
	v_mfma_f32_16x16x32_bf16 v[32:35], v[88:91], v[112:115], v[32:35]
	v_mfma_f32_16x16x32_bf16 v[36:39], v[88:91], v[116:119], v[36:39]
	v_mfma_f32_16x16x32_bf16 v[40:43], v[88:91], v[120:123], v[40:43]
	v_mfma_f32_16x16x32_bf16 v[44:47], v[88:91], v[124:127], v[44:47]
	s_waitcnt lgkmcnt(0)
	v_mfma_f32_16x16x32_bf16 v[48:51], v[92:95], v[112:115], v[48:51]
	v_mfma_f32_16x16x32_bf16 v[52:55], v[92:95], v[116:119], v[52:55]
	v_mfma_f32_16x16x32_bf16 v[56:59], v[92:95], v[120:123], v[56:59]
	v_mfma_f32_16x16x32_bf16 v[60:63], v[92:95], v[124:127], v[60:63]
	s_waitcnt vmcnt(0)
	s_barrier
	s_add_i32 s99, s99, 1
	s_cmp_eq_u32 s99, 16
	s_movk_i32 s0, 0x80
	s_cselect_b32 s0, 0xfffff880, s0
	s_cselect_b32 s99, 0, s99
	s_ashr_i32 s1, s0, 31
	s_add_u32 s26, s26, s0
	s_addc_u32 s27, s27, s1
	s_add_u32 s28, s28, s0
	s_addc_u32 s29, s29, s1
	s_mov_b32 m0, s7
	s_nop 0
	global_load_lds_dwordx4 v132, s[26:27] offset:0
	global_load_lds_dwordx4 v133, s[26:27] offset:1024
	global_load_lds_dwordx4 v134, s[26:27] offset:2048
	global_load_lds_dwordx4 v135, s[26:27] offset:3072
	s_mov_b32 m0, s8
	s_nop 0
	global_load_lds_dwordx4 v132, s[28:29] offset:0
	global_load_lds_dwordx4 v133, s[28:29] offset:1024
	global_load_lds_dwordx4 v134, s[28:29] offset:2048
	global_load_lds_dwordx4 v135, s[28:29] offset:3072
	ds_read_b128 v[64:67], v136 offset:0
	ds_read_b128 v[96:99], v140 offset:0
	ds_read_b128 v[100:103], v140 offset:2048
	ds_read_b128 v[104:107], v140 offset:4096
	ds_read_b128 v[108:111], v140 offset:6144
	ds_read_b128 v[68:71], v136 offset:2048
	ds_read_b128 v[72:75], v136 offset:4096
	ds_read_b128 v[76:79], v136 offset:6144
	s_waitcnt lgkmcnt(3)
	v_mfma_f32_16x16x32_bf16 v[0:3], v[64:67], v[96:99], v[0:3]
	v_mfma_f32_16x16x32_bf16 v[4:7], v[64:67], v[100:103], v[4:7]
	ds_read_b128 v[80:83], v137 offset:0
	v_mfma_f32_16x16x32_bf16 v[8:11], v[64:67], v[104:107], v[8:11]
	v_mfma_f32_16x16x32_bf16 v[12:15], v[64:67], v[108:111], v[12:15]
	ds_read_b128 v[112:115], v141 offset:0
	s_waitcnt lgkmcnt(4)
	v_mfma_f32_16x16x32_bf16 v[16:19], v[68:71], v[96:99], v[16:19]
	v_mfma_f32_16x16x32_bf16 v[20:23], v[68:71], v[100:103], v[20:23]
	ds_read_b128 v[116:119], v141 offset:2048
	v_mfma_f32_16x16x32_bf16 v[24:27], v[68:71], v[104:107], v[24:27]
	v_mfma_f32_16x16x32_bf16 v[28:31], v[68:71], v[108:111], v[28:31]
	ds_read_b128 v[120:123], v141 offset:4096
	s_waitcnt lgkmcnt(5)
	v_mfma_f32_16x16x32_bf16 v[32:35], v[72:75], v[96:99], v[32:35]
	v_mfma_f32_16x16x32_bf16 v[36:39], v[72:75], v[100:103], v[36:39]
	ds_read_b128 v[124:127], v141 offset:6144
	v_mfma_f32_16x16x32_bf16 v[40:43], v[72:75], v[104:107], v[40:43]
	v_mfma_f32_16x16x32_bf16 v[44:47], v[72:75], v[108:111], v[44:47]
	ds_read_b128 v[84:87], v137 offset:2048
	s_waitcnt lgkmcnt(6)
	v_mfma_f32_16x16x32_bf16 v[48:51], v[76:79], v[96:99], v[48:51]
	v_mfma_f32_16x16x32_bf16 v[52:55], v[76:79], v[100:103], v[52:55]
	ds_read_b128 v[88:91], v137 offset:4096
	v_mfma_f32_16x16x32_bf16 v[56:59], v[76:79], v[104:107], v[56:59]
	v_mfma_f32_16x16x32_bf16 v[60:63], v[76:79], v[108:111], v[60:63]
	ds_read_b128 v[92:95], v137 offset:6144
	s_waitcnt lgkmcnt(3)
	v_mfma_f32_16x16x32_bf16 v[0:3], v[80:83], v[112:115], v[0:3]
	v_mfma_f32_16x16x32_bf16 v[4:7], v[80:83], v[116:119], v[4:7]
	v_mfma_f32_16x16x32_bf16 v[8:11], v[80:83], v[120:123], v[8:11]
	v_mfma_f32_16x16x32_bf16 v[12:15], v[80:83], v[124:127], v[12:15]
	s_waitcnt lgkmcnt(2)
	v_mfma_f32_16x16x32_bf16 v[16:19], v[84:87], v[112:115], v[16:19]
	v_mfma_f32_16x16x32_bf16 v[20:23], v[84:87], v[116:119], v[20:23]
	v_mfma_f32_16x16x32_bf16 v[24:27], v[84:87], v[120:123], v[24:27]
	v_mfma_f32_16x16x32_bf16 v[28:31], v[84:87], v[124:127], v[28:31]
	s_waitcnt lgkmcnt(1)
	v_mfma_f32_16x16x32_bf16 v[32:35], v[88:91], v[112:115], v[32:35]
	v_mfma_f32_16x16x32_bf16 v[36:39], v[88:91], v[116:119], v[36:39]
	v_mfma_f32_16x16x32_bf16 v[40:43], v[88:91], v[120:123], v[40:43]
	v_mfma_f32_16x16x32_bf16 v[44:47], v[88:91], v[124:127], v[44:47]
	s_waitcnt lgkmcnt(0)
	v_mfma_f32_16x16x32_bf16 v[48:51], v[92:95], v[112:115], v[48:51]
	v_mfma_f32_16x16x32_bf16 v[52:55], v[92:95], v[116:119], v[52:55]
	v_mfma_f32_16x16x32_bf16 v[56:59], v[92:95], v[120:123], v[56:59]
	v_mfma_f32_16x16x32_bf16 v[60:63], v[92:95], v[124:127], v[60:63]
	s_waitcnt vmcnt(0)
	s_barrier
	s_add_i32 s99, s99, 1
	s_cmp_eq_u32 s99, 16
	s_movk_i32 s0, 0x80
	s_cselect_b32 s0, 0xfffff880, s0
	s_cselect_b32 s99, 0, s99
	s_ashr_i32 s1, s0, 31
	s_add_u32 s26, s26, s0
	s_addc_u32 s27, s27, s1
	s_add_u32 s28, s28, s0
	s_addc_u32 s29, s29, s1
	s_mov_b32 m0, s5
	s_nop 0
	global_load_lds_dwordx4 v132, s[26:27] offset:0
	global_load_lds_dwordx4 v133, s[26:27] offset:1024
	global_load_lds_dwordx4 v134, s[26:27] offset:2048
	global_load_lds_dwordx4 v135, s[26:27] offset:3072
	s_mov_b32 m0, s6
	s_nop 0
	global_load_lds_dwordx4 v132, s[28:29] offset:0
	global_load_lds_dwordx4 v133, s[28:29] offset:1024
	global_load_lds_dwordx4 v134, s[28:29] offset:2048
	global_load_lds_dwordx4 v135, s[28:29] offset:3072
	ds_read_b128 v[64:67], v138 offset:0
	ds_read_b128 v[96:99], v142 offset:0
	ds_read_b128 v[100:103], v142 offset:2048
	ds_read_b128 v[104:107], v142 offset:4096
	ds_read_b128 v[108:111], v142 offset:6144
	ds_read_b128 v[68:71], v138 offset:2048
	ds_read_b128 v[72:75], v138 offset:4096
	ds_read_b128 v[76:79], v138 offset:6144
	s_waitcnt lgkmcnt(3)
	v_mfma_f32_16x16x32_bf16 v[0:3], v[64:67], v[96:99], v[0:3]
	v_mfma_f32_16x16x32_bf16 v[4:7], v[64:67], v[100:103], v[4:7]
	ds_read_b128 v[80:83], v139 offset:0
	v_mfma_f32_16x16x32_bf16 v[8:11], v[64:67], v[104:107], v[8:11]
	v_mfma_f32_16x16x32_bf16 v[12:15], v[64:67], v[108:111], v[12:15]
	ds_read_b128 v[112:115], v143 offset:0
	s_waitcnt lgkmcnt(4)
	v_mfma_f32_16x16x32_bf16 v[16:19], v[68:71], v[96:99], v[16:19]
	v_mfma_f32_16x16x32_bf16 v[20:23], v[68:71], v[100:103], v[20:23]
	ds_read_b128 v[116:119], v143 offset:2048
	v_mfma_f32_16x16x32_bf16 v[24:27], v[68:71], v[104:107], v[24:27]
	v_mfma_f32_16x16x32_bf16 v[28:31], v[68:71], v[108:111], v[28:31]
	ds_read_b128 v[120:123], v143 offset:4096
	s_waitcnt lgkmcnt(5)
	v_mfma_f32_16x16x32_bf16 v[32:35], v[72:75], v[96:99], v[32:35]
	v_mfma_f32_16x16x32_bf16 v[36:39], v[72:75], v[100:103], v[36:39]
	ds_read_b128 v[124:127], v143 offset:6144
	v_mfma_f32_16x16x32_bf16 v[40:43], v[72:75], v[104:107], v[40:43]
	v_mfma_f32_16x16x32_bf16 v[44:47], v[72:75], v[108:111], v[44:47]
	ds_read_b128 v[84:87], v139 offset:2048
	s_waitcnt lgkmcnt(6)
	v_mfma_f32_16x16x32_bf16 v[48:51], v[76:79], v[96:99], v[48:51]
	v_mfma_f32_16x16x32_bf16 v[52:55], v[76:79], v[100:103], v[52:55]
	ds_read_b128 v[88:91], v139 offset:4096
	v_mfma_f32_16x16x32_bf16 v[56:59], v[76:79], v[104:107], v[56:59]
	v_mfma_f32_16x16x32_bf16 v[60:63], v[76:79], v[108:111], v[60:63]
	ds_read_b128 v[92:95], v139 offset:6144
	s_waitcnt lgkmcnt(3)
	v_mfma_f32_16x16x32_bf16 v[0:3], v[80:83], v[112:115], v[0:3]
	v_mfma_f32_16x16x32_bf16 v[4:7], v[80:83], v[116:119], v[4:7]
	v_mfma_f32_16x16x32_bf16 v[8:11], v[80:83], v[120:123], v[8:11]
	v_mfma_f32_16x16x32_bf16 v[12:15], v[80:83], v[124:127], v[12:15]
	s_waitcnt lgkmcnt(2)
	v_mfma_f32_16x16x32_bf16 v[16:19], v[84:87], v[112:115], v[16:19]
	v_mfma_f32_16x16x32_bf16 v[20:23], v[84:87], v[116:119], v[20:23]
	v_mfma_f32_16x16x32_bf16 v[24:27], v[84:87], v[120:123], v[24:27]
	v_mfma_f32_16x16x32_bf16 v[28:31], v[84:87], v[124:127], v[28:31]
	s_waitcnt lgkmcnt(1)
	v_mfma_f32_16x16x32_bf16 v[32:35], v[88:91], v[112:115], v[32:35]
	v_mfma_f32_16x16x32_bf16 v[36:39], v[88:91], v[116:119], v[36:39]
	v_mfma_f32_16x16x32_bf16 v[40:43], v[88:91], v[120:123], v[40:43]
	v_mfma_f32_16x16x32_bf16 v[44:47], v[88:91], v[124:127], v[44:47]
	s_waitcnt lgkmcnt(0)
	v_mfma_f32_16x16x32_bf16 v[48:51], v[92:95], v[112:115], v[48:51]
	v_mfma_f32_16x16x32_bf16 v[52:55], v[92:95], v[116:119], v[52:55]
	v_mfma_f32_16x16x32_bf16 v[56:59], v[92:95], v[120:123], v[56:59]
	v_mfma_f32_16x16x32_bf16 v[60:63], v[92:95], v[124:127], v[60:63]
	s_waitcnt vmcnt(0)
	s_barrier
	s_add_i32 s99, s99, 1
	s_cmp_eq_u32 s99, 16
	s_movk_i32 s0, 0x80
	s_cselect_b32 s0, 0xfffff880, s0
	s_cselect_b32 s99, 0, s99
	s_ashr_i32 s1, s0, 31
	s_add_u32 s26, s26, s0
	s_addc_u32 s27, s27, s1
	s_add_u32 s28, s28, s0
	s_addc_u32 s29, s29, s1
	s_mov_b32 m0, s7
	s_nop 0
	global_load_lds_dwordx4 v132, s[26:27] offset:0
	global_load_lds_dwordx4 v133, s[26:27] offset:1024
	global_load_lds_dwordx4 v134, s[26:27] offset:2048
	global_load_lds_dwordx4 v135, s[26:27] offset:3072
	s_mov_b32 m0, s8
	s_nop 0
	global_load_lds_dwordx4 v132, s[28:29] offset:0
	global_load_lds_dwordx4 v133, s[28:29] offset:1024
	global_load_lds_dwordx4 v134, s[28:29] offset:2048
	global_load_lds_dwordx4 v135, s[28:29] offset:3072
	ds_read_b128 v[64:67], v136 offset:0
	ds_read_b128 v[96:99], v140 offset:0
	ds_read_b128 v[100:103], v140 offset:2048
	ds_read_b128 v[104:107], v140 offset:4096
	ds_read_b128 v[108:111], v140 offset:6144
	ds_read_b128 v[68:71], v136 offset:2048
	ds_read_b128 v[72:75], v136 offset:4096
	ds_read_b128 v[76:79], v136 offset:6144
	s_waitcnt lgkmcnt(3)
	v_mfma_f32_16x16x32_bf16 v[0:3], v[64:67], v[96:99], v[0:3]
	v_mfma_f32_16x16x32_bf16 v[4:7], v[64:67], v[100:103], v[4:7]
	ds_read_b128 v[80:83], v137 offset:0
	v_mfma_f32_16x16x32_bf16 v[8:11], v[64:67], v[104:107], v[8:11]
	v_mfma_f32_16x16x32_bf16 v[12:15], v[64:67], v[108:111], v[12:15]
	ds_read_b128 v[112:115], v141 offset:0
	s_waitcnt lgkmcnt(4)
	v_mfma_f32_16x16x32_bf16 v[16:19], v[68:71], v[96:99], v[16:19]
	v_mfma_f32_16x16x32_bf16 v[20:23], v[68:71], v[100:103], v[20:23]
	ds_read_b128 v[116:119], v141 offset:2048
	v_mfma_f32_16x16x32_bf16 v[24:27], v[68:71], v[104:107], v[24:27]
	v_mfma_f32_16x16x32_bf16 v[28:31], v[68:71], v[108:111], v[28:31]
	ds_read_b128 v[120:123], v141 offset:4096
	s_waitcnt lgkmcnt(5)
	v_mfma_f32_16x16x32_bf16 v[32:35], v[72:75], v[96:99], v[32:35]
	v_mfma_f32_16x16x32_bf16 v[36:39], v[72:75], v[100:103], v[36:39]
	ds_read_b128 v[124:127], v141 offset:6144
	v_mfma_f32_16x16x32_bf16 v[40:43], v[72:75], v[104:107], v[40:43]
	v_mfma_f32_16x16x32_bf16 v[44:47], v[72:75], v[108:111], v[44:47]
	ds_read_b128 v[84:87], v137 offset:2048
	s_waitcnt lgkmcnt(6)
	v_mfma_f32_16x16x32_bf16 v[48:51], v[76:79], v[96:99], v[48:51]
	v_mfma_f32_16x16x32_bf16 v[52:55], v[76:79], v[100:103], v[52:55]
	ds_read_b128 v[88:91], v137 offset:4096
	v_mfma_f32_16x16x32_bf16 v[56:59], v[76:79], v[104:107], v[56:59]
	v_mfma_f32_16x16x32_bf16 v[60:63], v[76:79], v[108:111], v[60:63]
	ds_read_b128 v[92:95], v137 offset:6144
	s_waitcnt lgkmcnt(3)
	v_mfma_f32_16x16x32_bf16 v[0:3], v[80:83], v[112:115], v[0:3]
	v_mfma_f32_16x16x32_bf16 v[4:7], v[80:83], v[116:119], v[4:7]
	v_mfma_f32_16x16x32_bf16 v[8:11], v[80:83], v[120:123], v[8:11]
	v_mfma_f32_16x16x32_bf16 v[12:15], v[80:83], v[124:127], v[12:15]
	s_waitcnt lgkmcnt(2)
	v_mfma_f32_16x16x32_bf16 v[16:19], v[84:87], v[112:115], v[16:19]
	v_mfma_f32_16x16x32_bf16 v[20:23], v[84:87], v[116:119], v[20:23]
	v_mfma_f32_16x16x32_bf16 v[24:27], v[84:87], v[120:123], v[24:27]
	v_mfma_f32_16x16x32_bf16 v[28:31], v[84:87], v[124:127], v[28:31]
	s_waitcnt lgkmcnt(1)
	v_mfma_f32_16x16x32_bf16 v[32:35], v[88:91], v[112:115], v[32:35]
	v_mfma_f32_16x16x32_bf16 v[36:39], v[88:91], v[116:119], v[36:39]
	v_mfma_f32_16x16x32_bf16 v[40:43], v[88:91], v[120:123], v[40:43]
	v_mfma_f32_16x16x32_bf16 v[44:47], v[88:91], v[124:127], v[44:47]
	s_waitcnt lgkmcnt(0)
	v_mfma_f32_16x16x32_bf16 v[48:51], v[92:95], v[112:115], v[48:51]
	v_mfma_f32_16x16x32_bf16 v[52:55], v[92:95], v[116:119], v[52:55]
	v_mfma_f32_16x16x32_bf16 v[56:59], v[92:95], v[120:123], v[56:59]
	v_mfma_f32_16x16x32_bf16 v[60:63], v[92:95], v[124:127], v[60:63]
	s_waitcnt vmcnt(0)
	s_barrier
	s_add_i32 s99, s99, 1
	s_cmp_eq_u32 s99, 16
	s_movk_i32 s0, 0x80
	s_cselect_b32 s0, 0xfffff880, s0
	s_cselect_b32 s99, 0, s99
	s_ashr_i32 s1, s0, 31
	s_add_u32 s26, s26, s0
	s_addc_u32 s27, s27, s1
	s_add_u32 s28, s28, s0
	s_addc_u32 s29, s29, s1
	s_mov_b32 m0, s5
	s_nop 0
	global_load_lds_dwordx4 v132, s[26:27] offset:0
	global_load_lds_dwordx4 v133, s[26:27] offset:1024
	global_load_lds_dwordx4 v134, s[26:27] offset:2048
	global_load_lds_dwordx4 v135, s[26:27] offset:3072
	s_mov_b32 m0, s6
	s_nop 0
	global_load_lds_dwordx4 v132, s[28:29] offset:0
	global_load_lds_dwordx4 v133, s[28:29] offset:1024
	global_load_lds_dwordx4 v134, s[28:29] offset:2048
	global_load_lds_dwordx4 v135, s[28:29] offset:3072
	ds_read_b128 v[64:67], v138 offset:0
	ds_read_b128 v[96:99], v142 offset:0
	ds_read_b128 v[100:103], v142 offset:2048
	ds_read_b128 v[104:107], v142 offset:4096
	ds_read_b128 v[108:111], v142 offset:6144
	ds_read_b128 v[68:71], v138 offset:2048
	ds_read_b128 v[72:75], v138 offset:4096
	ds_read_b128 v[76:79], v138 offset:6144
	s_waitcnt lgkmcnt(3)
	v_mfma_f32_16x16x32_bf16 v[0:3], v[64:67], v[96:99], v[0:3]
	v_mfma_f32_16x16x32_bf16 v[4:7], v[64:67], v[100:103], v[4:7]
	ds_read_b128 v[80:83], v139 offset:0
	v_mfma_f32_16x16x32_bf16 v[8:11], v[64:67], v[104:107], v[8:11]
	v_mfma_f32_16x16x32_bf16 v[12:15], v[64:67], v[108:111], v[12:15]
	ds_read_b128 v[112:115], v143 offset:0
	s_waitcnt lgkmcnt(4)
	v_mfma_f32_16x16x32_bf16 v[16:19], v[68:71], v[96:99], v[16:19]
	v_mfma_f32_16x16x32_bf16 v[20:23], v[68:71], v[100:103], v[20:23]
	ds_read_b128 v[116:119], v143 offset:2048
	v_mfma_f32_16x16x32_bf16 v[24:27], v[68:71], v[104:107], v[24:27]
	v_mfma_f32_16x16x32_bf16 v[28:31], v[68:71], v[108:111], v[28:31]
	ds_read_b128 v[120:123], v143 offset:4096
	s_waitcnt lgkmcnt(5)
	v_mfma_f32_16x16x32_bf16 v[32:35], v[72:75], v[96:99], v[32:35]
	v_mfma_f32_16x16x32_bf16 v[36:39], v[72:75], v[100:103], v[36:39]
	ds_read_b128 v[124:127], v143 offset:6144
	v_mfma_f32_16x16x32_bf16 v[40:43], v[72:75], v[104:107], v[40:43]
	v_mfma_f32_16x16x32_bf16 v[44:47], v[72:75], v[108:111], v[44:47]
	ds_read_b128 v[84:87], v139 offset:2048
	s_waitcnt lgkmcnt(6)
	v_mfma_f32_16x16x32_bf16 v[48:51], v[76:79], v[96:99], v[48:51]
	v_mfma_f32_16x16x32_bf16 v[52:55], v[76:79], v[100:103], v[52:55]
	ds_read_b128 v[88:91], v139 offset:4096
	v_mfma_f32_16x16x32_bf16 v[56:59], v[76:79], v[104:107], v[56:59]
	v_mfma_f32_16x16x32_bf16 v[60:63], v[76:79], v[108:111], v[60:63]
	ds_read_b128 v[92:95], v139 offset:6144
	s_waitcnt lgkmcnt(3)
	v_mfma_f32_16x16x32_bf16 v[0:3], v[80:83], v[112:115], v[0:3]
	v_mfma_f32_16x16x32_bf16 v[4:7], v[80:83], v[116:119], v[4:7]
	v_mfma_f32_16x16x32_bf16 v[8:11], v[80:83], v[120:123], v[8:11]
	v_mfma_f32_16x16x32_bf16 v[12:15], v[80:83], v[124:127], v[12:15]
	s_waitcnt lgkmcnt(2)
	v_mfma_f32_16x16x32_bf16 v[16:19], v[84:87], v[112:115], v[16:19]
	v_mfma_f32_16x16x32_bf16 v[20:23], v[84:87], v[116:119], v[20:23]
	v_mfma_f32_16x16x32_bf16 v[24:27], v[84:87], v[120:123], v[24:27]
	v_mfma_f32_16x16x32_bf16 v[28:31], v[84:87], v[124:127], v[28:31]
	s_waitcnt lgkmcnt(1)
	v_mfma_f32_16x16x32_bf16 v[32:35], v[88:91], v[112:115], v[32:35]
	v_mfma_f32_16x16x32_bf16 v[36:39], v[88:91], v[116:119], v[36:39]
	v_mfma_f32_16x16x32_bf16 v[40:43], v[88:91], v[120:123], v[40:43]
	v_mfma_f32_16x16x32_bf16 v[44:47], v[88:91], v[124:127], v[44:47]
	s_waitcnt lgkmcnt(0)
	v_mfma_f32_16x16x32_bf16 v[48:51], v[92:95], v[112:115], v[48:51]
	v_mfma_f32_16x16x32_bf16 v[52:55], v[92:95], v[116:119], v[52:55]
	v_mfma_f32_16x16x32_bf16 v[56:59], v[92:95], v[120:123], v[56:59]
	v_mfma_f32_16x16x32_bf16 v[60:63], v[92:95], v[124:127], v[60:63]
	s_waitcnt vmcnt(0)
	s_barrier
	s_add_i32 s99, s99, 1
	s_cmp_eq_u32 s99, 16
	s_movk_i32 s0, 0x80
	s_cselect_b32 s0, 0xfffff880, s0
	s_cselect_b32 s99, 0, s99
	s_ashr_i32 s1, s0, 31
	s_add_u32 s26, s26, s0
	s_addc_u32 s27, s27, s1
	s_add_u32 s28, s28, s0
	s_addc_u32 s29, s29, s1
	s_mov_b32 m0, s7
	s_nop 0
	global_load_lds_dwordx4 v132, s[26:27] offset:0
	global_load_lds_dwordx4 v133, s[26:27] offset:1024
	global_load_lds_dwordx4 v134, s[26:27] offset:2048
	global_load_lds_dwordx4 v135, s[26:27] offset:3072
	s_mov_b32 m0, s8
	s_nop 0
	global_load_lds_dwordx4 v132, s[28:29] offset:0
	global_load_lds_dwordx4 v133, s[28:29] offset:1024
	global_load_lds_dwordx4 v134, s[28:29] offset:2048
	global_load_lds_dwordx4 v135, s[28:29] offset:3072
	ds_read_b128 v[64:67], v136 offset:0
	ds_read_b128 v[96:99], v140 offset:0
	ds_read_b128 v[100:103], v140 offset:2048
	ds_read_b128 v[104:107], v140 offset:4096
	ds_read_b128 v[108:111], v140 offset:6144
	ds_read_b128 v[68:71], v136 offset:2048
	ds_read_b128 v[72:75], v136 offset:4096
	ds_read_b128 v[76:79], v136 offset:6144
	s_waitcnt lgkmcnt(3)
	v_mfma_f32_16x16x32_bf16 v[0:3], v[64:67], v[96:99], v[0:3]
	v_mfma_f32_16x16x32_bf16 v[4:7], v[64:67], v[100:103], v[4:7]
	ds_read_b128 v[80:83], v137 offset:0
	v_mfma_f32_16x16x32_bf16 v[8:11], v[64:67], v[104:107], v[8:11]
	v_mfma_f32_16x16x32_bf16 v[12:15], v[64:67], v[108:111], v[12:15]
	ds_read_b128 v[112:115], v141 offset:0
	s_waitcnt lgkmcnt(4)
	v_mfma_f32_16x16x32_bf16 v[16:19], v[68:71], v[96:99], v[16:19]
	v_mfma_f32_16x16x32_bf16 v[20:23], v[68:71], v[100:103], v[20:23]
	ds_read_b128 v[116:119], v141 offset:2048
	v_mfma_f32_16x16x32_bf16 v[24:27], v[68:71], v[104:107], v[24:27]
	v_mfma_f32_16x16x32_bf16 v[28:31], v[68:71], v[108:111], v[28:31]
	ds_read_b128 v[120:123], v141 offset:4096
	s_waitcnt lgkmcnt(5)
	v_mfma_f32_16x16x32_bf16 v[32:35], v[72:75], v[96:99], v[32:35]
	v_mfma_f32_16x16x32_bf16 v[36:39], v[72:75], v[100:103], v[36:39]
	ds_read_b128 v[124:127], v141 offset:6144
	v_mfma_f32_16x16x32_bf16 v[40:43], v[72:75], v[104:107], v[40:43]
	v_mfma_f32_16x16x32_bf16 v[44:47], v[72:75], v[108:111], v[44:47]
	ds_read_b128 v[84:87], v137 offset:2048
	s_waitcnt lgkmcnt(6)
	v_mfma_f32_16x16x32_bf16 v[48:51], v[76:79], v[96:99], v[48:51]
	v_mfma_f32_16x16x32_bf16 v[52:55], v[76:79], v[100:103], v[52:55]
	ds_read_b128 v[88:91], v137 offset:4096
	v_mfma_f32_16x16x32_bf16 v[56:59], v[76:79], v[104:107], v[56:59]
	v_mfma_f32_16x16x32_bf16 v[60:63], v[76:79], v[108:111], v[60:63]
	ds_read_b128 v[92:95], v137 offset:6144
	s_waitcnt lgkmcnt(3)
	v_mfma_f32_16x16x32_bf16 v[0:3], v[80:83], v[112:115], v[0:3]
	v_mfma_f32_16x16x32_bf16 v[4:7], v[80:83], v[116:119], v[4:7]
	v_mfma_f32_16x16x32_bf16 v[8:11], v[80:83], v[120:123], v[8:11]
	v_mfma_f32_16x16x32_bf16 v[12:15], v[80:83], v[124:127], v[12:15]
	s_waitcnt lgkmcnt(2)
	v_mfma_f32_16x16x32_bf16 v[16:19], v[84:87], v[112:115], v[16:19]
	v_mfma_f32_16x16x32_bf16 v[20:23], v[84:87], v[116:119], v[20:23]
	v_mfma_f32_16x16x32_bf16 v[24:27], v[84:87], v[120:123], v[24:27]
	v_mfma_f32_16x16x32_bf16 v[28:31], v[84:87], v[124:127], v[28:31]
	s_waitcnt lgkmcnt(1)
	v_mfma_f32_16x16x32_bf16 v[32:35], v[88:91], v[112:115], v[32:35]
	v_mfma_f32_16x16x32_bf16 v[36:39], v[88:91], v[116:119], v[36:39]
	v_mfma_f32_16x16x32_bf16 v[40:43], v[88:91], v[120:123], v[40:43]
	v_mfma_f32_16x16x32_bf16 v[44:47], v[88:91], v[124:127], v[44:47]
	s_waitcnt lgkmcnt(0)
	v_mfma_f32_16x16x32_bf16 v[48:51], v[92:95], v[112:115], v[48:51]
	v_mfma_f32_16x16x32_bf16 v[52:55], v[92:95], v[116:119], v[52:55]
	v_mfma_f32_16x16x32_bf16 v[56:59], v[92:95], v[120:123], v[56:59]
	v_mfma_f32_16x16x32_bf16 v[60:63], v[92:95], v[124:127], v[60:63]
	s_waitcnt vmcnt(0)
	s_barrier
	s_add_i32 s99, s99, 1
	s_cmp_eq_u32 s99, 16
	s_movk_i32 s0, 0x80
	s_cselect_b32 s0, 0xfffff880, s0
	s_cselect_b32 s99, 0, s99
	s_ashr_i32 s1, s0, 31
	s_add_u32 s26, s26, s0
	s_addc_u32 s27, s27, s1
	s_add_u32 s28, s28, s0
	s_addc_u32 s29, s29, s1
	s_mov_b32 m0, s5
	s_nop 0
	global_load_lds_dwordx4 v132, s[26:27] offset:0
	global_load_lds_dwordx4 v133, s[26:27] offset:1024
	global_load_lds_dwordx4 v134, s[26:27] offset:2048
	global_load_lds_dwordx4 v135, s[26:27] offset:3072
	s_mov_b32 m0, s6
	s_nop 0
	global_load_lds_dwordx4 v132, s[28:29] offset:0
	global_load_lds_dwordx4 v133, s[28:29] offset:1024
	global_load_lds_dwordx4 v134, s[28:29] offset:2048
	global_load_lds_dwordx4 v135, s[28:29] offset:3072
	ds_read_b128 v[64:67], v138 offset:0
	ds_read_b128 v[96:99], v142 offset:0
	ds_read_b128 v[100:103], v142 offset:2048
	ds_read_b128 v[104:107], v142 offset:4096
	ds_read_b128 v[108:111], v142 offset:6144
	ds_read_b128 v[68:71], v138 offset:2048
	ds_read_b128 v[72:75], v138 offset:4096
	ds_read_b128 v[76:79], v138 offset:6144
	s_waitcnt lgkmcnt(3)
	v_mfma_f32_16x16x32_bf16 v[0:3], v[64:67], v[96:99], v[0:3]
	v_mfma_f32_16x16x32_bf16 v[4:7], v[64:67], v[100:103], v[4:7]
	ds_read_b128 v[80:83], v139 offset:0
	v_mfma_f32_16x16x32_bf16 v[8:11], v[64:67], v[104:107], v[8:11]
	v_mfma_f32_16x16x32_bf16 v[12:15], v[64:67], v[108:111], v[12:15]
	ds_read_b128 v[112:115], v143 offset:0
	s_waitcnt lgkmcnt(4)
	v_mfma_f32_16x16x32_bf16 v[16:19], v[68:71], v[96:99], v[16:19]
	v_mfma_f32_16x16x32_bf16 v[20:23], v[68:71], v[100:103], v[20:23]
	ds_read_b128 v[116:119], v143 offset:2048
	v_mfma_f32_16x16x32_bf16 v[24:27], v[68:71], v[104:107], v[24:27]
	v_mfma_f32_16x16x32_bf16 v[28:31], v[68:71], v[108:111], v[28:31]
	ds_read_b128 v[120:123], v143 offset:4096
	s_waitcnt lgkmcnt(5)
	v_mfma_f32_16x16x32_bf16 v[32:35], v[72:75], v[96:99], v[32:35]
	v_mfma_f32_16x16x32_bf16 v[36:39], v[72:75], v[100:103], v[36:39]
	ds_read_b128 v[124:127], v143 offset:6144
	v_mfma_f32_16x16x32_bf16 v[40:43], v[72:75], v[104:107], v[40:43]
	v_mfma_f32_16x16x32_bf16 v[44:47], v[72:75], v[108:111], v[44:47]
	ds_read_b128 v[84:87], v139 offset:2048
	s_waitcnt lgkmcnt(6)
	v_mfma_f32_16x16x32_bf16 v[48:51], v[76:79], v[96:99], v[48:51]
	v_mfma_f32_16x16x32_bf16 v[52:55], v[76:79], v[100:103], v[52:55]
	ds_read_b128 v[88:91], v139 offset:4096
	v_mfma_f32_16x16x32_bf16 v[56:59], v[76:79], v[104:107], v[56:59]
	v_mfma_f32_16x16x32_bf16 v[60:63], v[76:79], v[108:111], v[60:63]
	ds_read_b128 v[92:95], v139 offset:6144
	s_waitcnt lgkmcnt(3)
	v_mfma_f32_16x16x32_bf16 v[0:3], v[80:83], v[112:115], v[0:3]
	v_mfma_f32_16x16x32_bf16 v[4:7], v[80:83], v[116:119], v[4:7]
	v_mfma_f32_16x16x32_bf16 v[8:11], v[80:83], v[120:123], v[8:11]
	v_mfma_f32_16x16x32_bf16 v[12:15], v[80:83], v[124:127], v[12:15]
	s_waitcnt lgkmcnt(2)
	v_mfma_f32_16x16x32_bf16 v[16:19], v[84:87], v[112:115], v[16:19]
	v_mfma_f32_16x16x32_bf16 v[20:23], v[84:87], v[116:119], v[20:23]
	v_mfma_f32_16x16x32_bf16 v[24:27], v[84:87], v[120:123], v[24:27]
	v_mfma_f32_16x16x32_bf16 v[28:31], v[84:87], v[124:127], v[28:31]
	s_waitcnt lgkmcnt(1)
	v_mfma_f32_16x16x32_bf16 v[32:35], v[88:91], v[112:115], v[32:35]
	v_mfma_f32_16x16x32_bf16 v[36:39], v[88:91], v[116:119], v[36:39]
	v_mfma_f32_16x16x32_bf16 v[40:43], v[88:91], v[120:123], v[40:43]
	v_mfma_f32_16x16x32_bf16 v[44:47], v[88:91], v[124:127], v[44:47]
	s_waitcnt lgkmcnt(0)
	v_mfma_f32_16x16x32_bf16 v[48:51], v[92:95], v[112:115], v[48:51]
	v_mfma_f32_16x16x32_bf16 v[52:55], v[92:95], v[116:119], v[52:55]
	v_mfma_f32_16x16x32_bf16 v[56:59], v[92:95], v[120:123], v[56:59]
	v_mfma_f32_16x16x32_bf16 v[60:63], v[92:95], v[124:127], v[60:63]
	s_waitcnt vmcnt(0)
	s_barrier
	s_add_i32 s99, s99, 1
	s_cmp_eq_u32 s99, 16
	s_movk_i32 s0, 0x80
	s_cselect_b32 s0, 0xfffff880, s0
	s_cselect_b32 s99, 0, s99
	s_ashr_i32 s1, s0, 31
	s_add_u32 s26, s26, s0
	s_addc_u32 s27, s27, s1
	s_add_u32 s28, s28, s0
	s_addc_u32 s29, s29, s1
	s_mov_b32 m0, s7
	s_nop 0
	global_load_lds_dwordx4 v132, s[26:27] offset:0
	global_load_lds_dwordx4 v133, s[26:27] offset:1024
	global_load_lds_dwordx4 v134, s[26:27] offset:2048
	global_load_lds_dwordx4 v135, s[26:27] offset:3072
	s_mov_b32 m0, s8
	s_nop 0
	global_load_lds_dwordx4 v132, s[28:29] offset:0
	global_load_lds_dwordx4 v133, s[28:29] offset:1024
	global_load_lds_dwordx4 v134, s[28:29] offset:2048
	global_load_lds_dwordx4 v135, s[28:29] offset:3072
	ds_read_b128 v[64:67], v136 offset:0
	ds_read_b128 v[96:99], v140 offset:0
	ds_read_b128 v[100:103], v140 offset:2048
	ds_read_b128 v[104:107], v140 offset:4096
	ds_read_b128 v[108:111], v140 offset:6144
	ds_read_b128 v[68:71], v136 offset:2048
	ds_read_b128 v[72:75], v136 offset:4096
	ds_read_b128 v[76:79], v136 offset:6144
	s_waitcnt lgkmcnt(3)
	v_mfma_f32_16x16x32_bf16 v[0:3], v[64:67], v[96:99], v[0:3]
	v_mfma_f32_16x16x32_bf16 v[4:7], v[64:67], v[100:103], v[4:7]
	ds_read_b128 v[80:83], v137 offset:0
	v_mfma_f32_16x16x32_bf16 v[8:11], v[64:67], v[104:107], v[8:11]
	v_mfma_f32_16x16x32_bf16 v[12:15], v[64:67], v[108:111], v[12:15]
	ds_read_b128 v[112:115], v141 offset:0
	s_waitcnt lgkmcnt(4)
	v_mfma_f32_16x16x32_bf16 v[16:19], v[68:71], v[96:99], v[16:19]
	v_mfma_f32_16x16x32_bf16 v[20:23], v[68:71], v[100:103], v[20:23]
	ds_read_b128 v[116:119], v141 offset:2048
	v_mfma_f32_16x16x32_bf16 v[24:27], v[68:71], v[104:107], v[24:27]
	v_mfma_f32_16x16x32_bf16 v[28:31], v[68:71], v[108:111], v[28:31]
	ds_read_b128 v[120:123], v141 offset:4096
	s_waitcnt lgkmcnt(5)
	v_mfma_f32_16x16x32_bf16 v[32:35], v[72:75], v[96:99], v[32:35]
	v_mfma_f32_16x16x32_bf16 v[36:39], v[72:75], v[100:103], v[36:39]
	ds_read_b128 v[124:127], v141 offset:6144
	v_mfma_f32_16x16x32_bf16 v[40:43], v[72:75], v[104:107], v[40:43]
	v_mfma_f32_16x16x32_bf16 v[44:47], v[72:75], v[108:111], v[44:47]
	ds_read_b128 v[84:87], v137 offset:2048
	s_waitcnt lgkmcnt(6)
	v_mfma_f32_16x16x32_bf16 v[48:51], v[76:79], v[96:99], v[48:51]
	v_mfma_f32_16x16x32_bf16 v[52:55], v[76:79], v[100:103], v[52:55]
	ds_read_b128 v[88:91], v137 offset:4096
	v_mfma_f32_16x16x32_bf16 v[56:59], v[76:79], v[104:107], v[56:59]
	v_mfma_f32_16x16x32_bf16 v[60:63], v[76:79], v[108:111], v[60:63]
	ds_read_b128 v[92:95], v137 offset:6144
	s_waitcnt lgkmcnt(3)
	v_mfma_f32_16x16x32_bf16 v[0:3], v[80:83], v[112:115], v[0:3]
	v_mfma_f32_16x16x32_bf16 v[4:7], v[80:83], v[116:119], v[4:7]
	v_mfma_f32_16x16x32_bf16 v[8:11], v[80:83], v[120:123], v[8:11]
	v_mfma_f32_16x16x32_bf16 v[12:15], v[80:83], v[124:127], v[12:15]
	s_waitcnt lgkmcnt(2)
	v_mfma_f32_16x16x32_bf16 v[16:19], v[84:87], v[112:115], v[16:19]
	v_mfma_f32_16x16x32_bf16 v[20:23], v[84:87], v[116:119], v[20:23]
	v_mfma_f32_16x16x32_bf16 v[24:27], v[84:87], v[120:123], v[24:27]
	v_mfma_f32_16x16x32_bf16 v[28:31], v[84:87], v[124:127], v[28:31]
	s_waitcnt lgkmcnt(1)
	v_mfma_f32_16x16x32_bf16 v[32:35], v[88:91], v[112:115], v[32:35]
	v_mfma_f32_16x16x32_bf16 v[36:39], v[88:91], v[116:119], v[36:39]
	v_mfma_f32_16x16x32_bf16 v[40:43], v[88:91], v[120:123], v[40:43]
	v_mfma_f32_16x16x32_bf16 v[44:47], v[88:91], v[124:127], v[44:47]
	s_waitcnt lgkmcnt(0)
	v_mfma_f32_16x16x32_bf16 v[48:51], v[92:95], v[112:115], v[48:51]
	v_mfma_f32_16x16x32_bf16 v[52:55], v[92:95], v[116:119], v[52:55]
	v_mfma_f32_16x16x32_bf16 v[56:59], v[92:95], v[120:123], v[56:59]
	v_mfma_f32_16x16x32_bf16 v[60:63], v[92:95], v[124:127], v[60:63]
	s_waitcnt vmcnt(0)
	s_barrier
	s_add_i32 s99, s99, 1
	s_cmp_eq_u32 s99, 16
	s_movk_i32 s0, 0x80
	s_cselect_b32 s0, 0xfffff880, s0
	s_cselect_b32 s99, 0, s99
	s_ashr_i32 s1, s0, 31
	s_add_u32 s26, s26, s0
	s_addc_u32 s27, s27, s1
	s_add_u32 s28, s28, s0
	s_addc_u32 s29, s29, s1
	s_mov_b32 m0, s5
	s_nop 0
	global_load_lds_dwordx4 v132, s[26:27] offset:0
	global_load_lds_dwordx4 v133, s[26:27] offset:1024
	global_load_lds_dwordx4 v134, s[26:27] offset:2048
	global_load_lds_dwordx4 v135, s[26:27] offset:3072
	s_mov_b32 m0, s6
	s_nop 0
	global_load_lds_dwordx4 v132, s[28:29] offset:0
	global_load_lds_dwordx4 v133, s[28:29] offset:1024
	global_load_lds_dwordx4 v134, s[28:29] offset:2048
	global_load_lds_dwordx4 v135, s[28:29] offset:3072
	ds_read_b128 v[64:67], v138 offset:0
	ds_read_b128 v[96:99], v142 offset:0
	ds_read_b128 v[100:103], v142 offset:2048
	ds_read_b128 v[104:107], v142 offset:4096
	ds_read_b128 v[108:111], v142 offset:6144
	ds_read_b128 v[68:71], v138 offset:2048
	ds_read_b128 v[72:75], v138 offset:4096
	ds_read_b128 v[76:79], v138 offset:6144
	s_waitcnt lgkmcnt(3)
	v_mfma_f32_16x16x32_bf16 v[0:3], v[64:67], v[96:99], v[0:3]
	v_mfma_f32_16x16x32_bf16 v[4:7], v[64:67], v[100:103], v[4:7]
	ds_read_b128 v[80:83], v139 offset:0
	v_mfma_f32_16x16x32_bf16 v[8:11], v[64:67], v[104:107], v[8:11]
	v_mfma_f32_16x16x32_bf16 v[12:15], v[64:67], v[108:111], v[12:15]
	ds_read_b128 v[112:115], v143 offset:0
	s_waitcnt lgkmcnt(4)
	v_mfma_f32_16x16x32_bf16 v[16:19], v[68:71], v[96:99], v[16:19]
	v_mfma_f32_16x16x32_bf16 v[20:23], v[68:71], v[100:103], v[20:23]
	ds_read_b128 v[116:119], v143 offset:2048
	v_mfma_f32_16x16x32_bf16 v[24:27], v[68:71], v[104:107], v[24:27]
	v_mfma_f32_16x16x32_bf16 v[28:31], v[68:71], v[108:111], v[28:31]
	ds_read_b128 v[120:123], v143 offset:4096
	s_waitcnt lgkmcnt(5)
	v_mfma_f32_16x16x32_bf16 v[32:35], v[72:75], v[96:99], v[32:35]
	v_mfma_f32_16x16x32_bf16 v[36:39], v[72:75], v[100:103], v[36:39]
	ds_read_b128 v[124:127], v143 offset:6144
	v_mfma_f32_16x16x32_bf16 v[40:43], v[72:75], v[104:107], v[40:43]
	v_mfma_f32_16x16x32_bf16 v[44:47], v[72:75], v[108:111], v[44:47]
	ds_read_b128 v[84:87], v139 offset:2048
	s_waitcnt lgkmcnt(6)
	v_mfma_f32_16x16x32_bf16 v[48:51], v[76:79], v[96:99], v[48:51]
	v_mfma_f32_16x16x32_bf16 v[52:55], v[76:79], v[100:103], v[52:55]
	ds_read_b128 v[88:91], v139 offset:4096
	v_mfma_f32_16x16x32_bf16 v[56:59], v[76:79], v[104:107], v[56:59]
	v_mfma_f32_16x16x32_bf16 v[60:63], v[76:79], v[108:111], v[60:63]
	ds_read_b128 v[92:95], v139 offset:6144
	s_waitcnt lgkmcnt(3)
	v_mfma_f32_16x16x32_bf16 v[0:3], v[80:83], v[112:115], v[0:3]
	v_mfma_f32_16x16x32_bf16 v[4:7], v[80:83], v[116:119], v[4:7]
	v_mfma_f32_16x16x32_bf16 v[8:11], v[80:83], v[120:123], v[8:11]
	v_mfma_f32_16x16x32_bf16 v[12:15], v[80:83], v[124:127], v[12:15]
	s_waitcnt lgkmcnt(2)
	v_mfma_f32_16x16x32_bf16 v[16:19], v[84:87], v[112:115], v[16:19]
	v_mfma_f32_16x16x32_bf16 v[20:23], v[84:87], v[116:119], v[20:23]
	v_mfma_f32_16x16x32_bf16 v[24:27], v[84:87], v[120:123], v[24:27]
	v_mfma_f32_16x16x32_bf16 v[28:31], v[84:87], v[124:127], v[28:31]
	s_waitcnt lgkmcnt(1)
	v_mfma_f32_16x16x32_bf16 v[32:35], v[88:91], v[112:115], v[32:35]
	v_mfma_f32_16x16x32_bf16 v[36:39], v[88:91], v[116:119], v[36:39]
	v_mfma_f32_16x16x32_bf16 v[40:43], v[88:91], v[120:123], v[40:43]
	v_mfma_f32_16x16x32_bf16 v[44:47], v[88:91], v[124:127], v[44:47]
	s_waitcnt lgkmcnt(0)
	v_mfma_f32_16x16x32_bf16 v[48:51], v[92:95], v[112:115], v[48:51]
	v_mfma_f32_16x16x32_bf16 v[52:55], v[92:95], v[116:119], v[52:55]
	v_mfma_f32_16x16x32_bf16 v[56:59], v[92:95], v[120:123], v[56:59]
	v_mfma_f32_16x16x32_bf16 v[60:63], v[92:95], v[124:127], v[60:63]
	s_waitcnt vmcnt(0)
	s_barrier
	s_add_i32 s99, s99, 1
	s_cmp_eq_u32 s99, 16
	s_movk_i32 s0, 0x80
	s_cselect_b32 s0, 0xfffff880, s0
	s_cselect_b32 s99, 0, s99
	s_ashr_i32 s1, s0, 31
	s_add_u32 s26, s26, s0
	s_addc_u32 s27, s27, s1
	s_add_u32 s28, s28, s0
	s_addc_u32 s29, s29, s1
	s_mov_b32 m0, s7
	s_nop 0
	global_load_lds_dwordx4 v132, s[26:27] offset:0
	global_load_lds_dwordx4 v133, s[26:27] offset:1024
	global_load_lds_dwordx4 v134, s[26:27] offset:2048
	global_load_lds_dwordx4 v135, s[26:27] offset:3072
	s_mov_b32 m0, s8
	s_nop 0
	global_load_lds_dwordx4 v132, s[28:29] offset:0
	global_load_lds_dwordx4 v133, s[28:29] offset:1024
	global_load_lds_dwordx4 v134, s[28:29] offset:2048
	global_load_lds_dwordx4 v135, s[28:29] offset:3072
	ds_read_b128 v[64:67], v136 offset:0
	ds_read_b128 v[96:99], v140 offset:0
	ds_read_b128 v[100:103], v140 offset:2048
	ds_read_b128 v[104:107], v140 offset:4096
	ds_read_b128 v[108:111], v140 offset:6144
	ds_read_b128 v[68:71], v136 offset:2048
	ds_read_b128 v[72:75], v136 offset:4096
	ds_read_b128 v[76:79], v136 offset:6144
	s_waitcnt lgkmcnt(3)
	v_mfma_f32_16x16x32_bf16 v[0:3], v[64:67], v[96:99], v[0:3]
	v_mfma_f32_16x16x32_bf16 v[4:7], v[64:67], v[100:103], v[4:7]
	ds_read_b128 v[80:83], v137 offset:0
	v_mfma_f32_16x16x32_bf16 v[8:11], v[64:67], v[104:107], v[8:11]
	v_mfma_f32_16x16x32_bf16 v[12:15], v[64:67], v[108:111], v[12:15]
	ds_read_b128 v[112:115], v141 offset:0
	s_waitcnt lgkmcnt(4)
	v_mfma_f32_16x16x32_bf16 v[16:19], v[68:71], v[96:99], v[16:19]
	v_mfma_f32_16x16x32_bf16 v[20:23], v[68:71], v[100:103], v[20:23]
	ds_read_b128 v[116:119], v141 offset:2048
	v_mfma_f32_16x16x32_bf16 v[24:27], v[68:71], v[104:107], v[24:27]
	v_mfma_f32_16x16x32_bf16 v[28:31], v[68:71], v[108:111], v[28:31]
	ds_read_b128 v[120:123], v141 offset:4096
	s_waitcnt lgkmcnt(5)
	v_mfma_f32_16x16x32_bf16 v[32:35], v[72:75], v[96:99], v[32:35]
	v_mfma_f32_16x16x32_bf16 v[36:39], v[72:75], v[100:103], v[36:39]
	ds_read_b128 v[124:127], v141 offset:6144
	v_mfma_f32_16x16x32_bf16 v[40:43], v[72:75], v[104:107], v[40:43]
	v_mfma_f32_16x16x32_bf16 v[44:47], v[72:75], v[108:111], v[44:47]
	ds_read_b128 v[84:87], v137 offset:2048
	s_waitcnt lgkmcnt(6)
	v_mfma_f32_16x16x32_bf16 v[48:51], v[76:79], v[96:99], v[48:51]
	v_mfma_f32_16x16x32_bf16 v[52:55], v[76:79], v[100:103], v[52:55]
	ds_read_b128 v[88:91], v137 offset:4096
	v_mfma_f32_16x16x32_bf16 v[56:59], v[76:79], v[104:107], v[56:59]
	v_mfma_f32_16x16x32_bf16 v[60:63], v[76:79], v[108:111], v[60:63]
	ds_read_b128 v[92:95], v137 offset:6144
	s_waitcnt lgkmcnt(3)
	v_mfma_f32_16x16x32_bf16 v[0:3], v[80:83], v[112:115], v[0:3]
	v_mfma_f32_16x16x32_bf16 v[4:7], v[80:83], v[116:119], v[4:7]
	v_mfma_f32_16x16x32_bf16 v[8:11], v[80:83], v[120:123], v[8:11]
	v_mfma_f32_16x16x32_bf16 v[12:15], v[80:83], v[124:127], v[12:15]
	s_waitcnt lgkmcnt(2)
	v_mfma_f32_16x16x32_bf16 v[16:19], v[84:87], v[112:115], v[16:19]
	v_mfma_f32_16x16x32_bf16 v[20:23], v[84:87], v[116:119], v[20:23]
	v_mfma_f32_16x16x32_bf16 v[24:27], v[84:87], v[120:123], v[24:27]
	v_mfma_f32_16x16x32_bf16 v[28:31], v[84:87], v[124:127], v[28:31]
	s_waitcnt lgkmcnt(1)
	v_mfma_f32_16x16x32_bf16 v[32:35], v[88:91], v[112:115], v[32:35]
	v_mfma_f32_16x16x32_bf16 v[36:39], v[88:91], v[116:119], v[36:39]
	v_mfma_f32_16x16x32_bf16 v[40:43], v[88:91], v[120:123], v[40:43]
	v_mfma_f32_16x16x32_bf16 v[44:47], v[88:91], v[124:127], v[44:47]
	s_waitcnt lgkmcnt(0)
	v_mfma_f32_16x16x32_bf16 v[48:51], v[92:95], v[112:115], v[48:51]
	v_mfma_f32_16x16x32_bf16 v[52:55], v[92:95], v[116:119], v[52:55]
	v_mfma_f32_16x16x32_bf16 v[56:59], v[92:95], v[120:123], v[56:59]
	v_mfma_f32_16x16x32_bf16 v[60:63], v[92:95], v[124:127], v[60:63]
	s_waitcnt vmcnt(0)
	s_barrier
	s_add_i32 s99, s99, 1
	s_cmp_eq_u32 s99, 16
	s_movk_i32 s0, 0x80
	s_cselect_b32 s0, 0xfffff880, s0
	s_cselect_b32 s99, 0, s99
	s_ashr_i32 s1, s0, 31
	s_add_u32 s26, s26, s0
	s_addc_u32 s27, s27, s1
	s_add_u32 s28, s28, s0
	s_addc_u32 s29, s29, s1
	s_mov_b32 m0, s5
	s_nop 0
	global_load_lds_dwordx4 v132, s[26:27] offset:0
	global_load_lds_dwordx4 v133, s[26:27] offset:1024
	global_load_lds_dwordx4 v134, s[26:27] offset:2048
	global_load_lds_dwordx4 v135, s[26:27] offset:3072
	s_mov_b32 m0, s6
	s_nop 0
	global_load_lds_dwordx4 v132, s[28:29] offset:0
	global_load_lds_dwordx4 v133, s[28:29] offset:1024
	global_load_lds_dwordx4 v134, s[28:29] offset:2048
	global_load_lds_dwordx4 v135, s[28:29] offset:3072
	ds_read_b128 v[64:67], v138 offset:0
	ds_read_b128 v[96:99], v142 offset:0
	ds_read_b128 v[100:103], v142 offset:2048
	ds_read_b128 v[104:107], v142 offset:4096
	ds_read_b128 v[108:111], v142 offset:6144
	ds_read_b128 v[68:71], v138 offset:2048
	ds_read_b128 v[72:75], v138 offset:4096
	ds_read_b128 v[76:79], v138 offset:6144
	s_waitcnt lgkmcnt(3)
	v_mfma_f32_16x16x32_bf16 v[0:3], v[64:67], v[96:99], v[0:3]
	v_mfma_f32_16x16x32_bf16 v[4:7], v[64:67], v[100:103], v[4:7]
	ds_read_b128 v[80:83], v139 offset:0
	v_mfma_f32_16x16x32_bf16 v[8:11], v[64:67], v[104:107], v[8:11]
	v_mfma_f32_16x16x32_bf16 v[12:15], v[64:67], v[108:111], v[12:15]
	ds_read_b128 v[112:115], v143 offset:0
	s_waitcnt lgkmcnt(4)
	v_mfma_f32_16x16x32_bf16 v[16:19], v[68:71], v[96:99], v[16:19]
	v_mfma_f32_16x16x32_bf16 v[20:23], v[68:71], v[100:103], v[20:23]
	ds_read_b128 v[116:119], v143 offset:2048
	v_mfma_f32_16x16x32_bf16 v[24:27], v[68:71], v[104:107], v[24:27]
	v_mfma_f32_16x16x32_bf16 v[28:31], v[68:71], v[108:111], v[28:31]
	ds_read_b128 v[120:123], v143 offset:4096
	s_waitcnt lgkmcnt(5)
	v_mfma_f32_16x16x32_bf16 v[32:35], v[72:75], v[96:99], v[32:35]
	v_mfma_f32_16x16x32_bf16 v[36:39], v[72:75], v[100:103], v[36:39]
	ds_read_b128 v[124:127], v143 offset:6144
	v_mfma_f32_16x16x32_bf16 v[40:43], v[72:75], v[104:107], v[40:43]
	v_mfma_f32_16x16x32_bf16 v[44:47], v[72:75], v[108:111], v[44:47]
	ds_read_b128 v[84:87], v139 offset:2048
	s_waitcnt lgkmcnt(6)
	v_mfma_f32_16x16x32_bf16 v[48:51], v[76:79], v[96:99], v[48:51]
	v_mfma_f32_16x16x32_bf16 v[52:55], v[76:79], v[100:103], v[52:55]
	ds_read_b128 v[88:91], v139 offset:4096
	v_mfma_f32_16x16x32_bf16 v[56:59], v[76:79], v[104:107], v[56:59]
	v_mfma_f32_16x16x32_bf16 v[60:63], v[76:79], v[108:111], v[60:63]
	ds_read_b128 v[92:95], v139 offset:6144
	s_waitcnt lgkmcnt(3)
	v_mfma_f32_16x16x32_bf16 v[0:3], v[80:83], v[112:115], v[0:3]
	v_mfma_f32_16x16x32_bf16 v[4:7], v[80:83], v[116:119], v[4:7]
	v_mfma_f32_16x16x32_bf16 v[8:11], v[80:83], v[120:123], v[8:11]
	v_mfma_f32_16x16x32_bf16 v[12:15], v[80:83], v[124:127], v[12:15]
	s_waitcnt lgkmcnt(2)
	v_mfma_f32_16x16x32_bf16 v[16:19], v[84:87], v[112:115], v[16:19]
	v_mfma_f32_16x16x32_bf16 v[20:23], v[84:87], v[116:119], v[20:23]
	v_mfma_f32_16x16x32_bf16 v[24:27], v[84:87], v[120:123], v[24:27]
	v_mfma_f32_16x16x32_bf16 v[28:31], v[84:87], v[124:127], v[28:31]
	s_waitcnt lgkmcnt(1)
	v_mfma_f32_16x16x32_bf16 v[32:35], v[88:91], v[112:115], v[32:35]
	v_mfma_f32_16x16x32_bf16 v[36:39], v[88:91], v[116:119], v[36:39]
	v_mfma_f32_16x16x32_bf16 v[40:43], v[88:91], v[120:123], v[40:43]
	v_mfma_f32_16x16x32_bf16 v[44:47], v[88:91], v[124:127], v[44:47]
	s_waitcnt lgkmcnt(0)
	v_mfma_f32_16x16x32_bf16 v[48:51], v[92:95], v[112:115], v[48:51]
	v_mfma_f32_16x16x32_bf16 v[52:55], v[92:95], v[116:119], v[52:55]
	v_mfma_f32_16x16x32_bf16 v[56:59], v[92:95], v[120:123], v[56:59]
	v_mfma_f32_16x16x32_bf16 v[60:63], v[92:95], v[124:127], v[60:63]
	s_waitcnt vmcnt(0)
	s_barrier
	s_add_i32 s99, s99, 1
	s_cmp_eq_u32 s99, 16
	s_movk_i32 s0, 0x80
	s_cselect_b32 s0, 0xfffff880, s0
	s_cselect_b32 s99, 0, s99
	s_ashr_i32 s1, s0, 31
	s_add_u32 s26, s26, s0
	s_addc_u32 s27, s27, s1
	s_add_u32 s28, s28, s0
	s_addc_u32 s29, s29, s1
	s_mov_b32 m0, s7
	s_nop 0
	global_load_lds_dwordx4 v132, s[26:27] offset:0
	global_load_lds_dwordx4 v133, s[26:27] offset:1024
	global_load_lds_dwordx4 v134, s[26:27] offset:2048
	global_load_lds_dwordx4 v135, s[26:27] offset:3072
	s_mov_b32 m0, s8
	s_nop 0
	global_load_lds_dwordx4 v132, s[28:29] offset:0
	global_load_lds_dwordx4 v133, s[28:29] offset:1024
	global_load_lds_dwordx4 v134, s[28:29] offset:2048
	global_load_lds_dwordx4 v135, s[28:29] offset:3072
	ds_read_b128 v[64:67], v136 offset:0
	ds_read_b128 v[96:99], v140 offset:0
	ds_read_b128 v[100:103], v140 offset:2048
	ds_read_b128 v[104:107], v140 offset:4096
	ds_read_b128 v[108:111], v140 offset:6144
	ds_read_b128 v[68:71], v136 offset:2048
	ds_read_b128 v[72:75], v136 offset:4096
	ds_read_b128 v[76:79], v136 offset:6144
	s_waitcnt lgkmcnt(3)
	v_mfma_f32_16x16x32_bf16 v[0:3], v[64:67], v[96:99], v[0:3]
	v_mfma_f32_16x16x32_bf16 v[4:7], v[64:67], v[100:103], v[4:7]
	ds_read_b128 v[80:83], v137 offset:0
	v_mfma_f32_16x16x32_bf16 v[8:11], v[64:67], v[104:107], v[8:11]
	v_mfma_f32_16x16x32_bf16 v[12:15], v[64:67], v[108:111], v[12:15]
	ds_read_b128 v[112:115], v141 offset:0
	s_waitcnt lgkmcnt(4)
	v_mfma_f32_16x16x32_bf16 v[16:19], v[68:71], v[96:99], v[16:19]
	v_mfma_f32_16x16x32_bf16 v[20:23], v[68:71], v[100:103], v[20:23]
	ds_read_b128 v[116:119], v141 offset:2048
	v_mfma_f32_16x16x32_bf16 v[24:27], v[68:71], v[104:107], v[24:27]
	v_mfma_f32_16x16x32_bf16 v[28:31], v[68:71], v[108:111], v[28:31]
	ds_read_b128 v[120:123], v141 offset:4096
	s_waitcnt lgkmcnt(5)
	v_mfma_f32_16x16x32_bf16 v[32:35], v[72:75], v[96:99], v[32:35]
	v_mfma_f32_16x16x32_bf16 v[36:39], v[72:75], v[100:103], v[36:39]
	ds_read_b128 v[124:127], v141 offset:6144
	v_mfma_f32_16x16x32_bf16 v[40:43], v[72:75], v[104:107], v[40:43]
	v_mfma_f32_16x16x32_bf16 v[44:47], v[72:75], v[108:111], v[44:47]
	ds_read_b128 v[84:87], v137 offset:2048
	s_waitcnt lgkmcnt(6)
	v_mfma_f32_16x16x32_bf16 v[48:51], v[76:79], v[96:99], v[48:51]
	v_mfma_f32_16x16x32_bf16 v[52:55], v[76:79], v[100:103], v[52:55]
	ds_read_b128 v[88:91], v137 offset:4096
	v_mfma_f32_16x16x32_bf16 v[56:59], v[76:79], v[104:107], v[56:59]
	v_mfma_f32_16x16x32_bf16 v[60:63], v[76:79], v[108:111], v[60:63]
	ds_read_b128 v[92:95], v137 offset:6144
	s_waitcnt lgkmcnt(3)
	v_mfma_f32_16x16x32_bf16 v[0:3], v[80:83], v[112:115], v[0:3]
	v_mfma_f32_16x16x32_bf16 v[4:7], v[80:83], v[116:119], v[4:7]
	v_mfma_f32_16x16x32_bf16 v[8:11], v[80:83], v[120:123], v[8:11]
	v_mfma_f32_16x16x32_bf16 v[12:15], v[80:83], v[124:127], v[12:15]
	s_waitcnt lgkmcnt(2)
	v_mfma_f32_16x16x32_bf16 v[16:19], v[84:87], v[112:115], v[16:19]
	v_mfma_f32_16x16x32_bf16 v[20:23], v[84:87], v[116:119], v[20:23]
	v_mfma_f32_16x16x32_bf16 v[24:27], v[84:87], v[120:123], v[24:27]
	v_mfma_f32_16x16x32_bf16 v[28:31], v[84:87], v[124:127], v[28:31]
	s_waitcnt lgkmcnt(1)
	v_mfma_f32_16x16x32_bf16 v[32:35], v[88:91], v[112:115], v[32:35]
	v_mfma_f32_16x16x32_bf16 v[36:39], v[88:91], v[116:119], v[36:39]
	v_mfma_f32_16x16x32_bf16 v[40:43], v[88:91], v[120:123], v[40:43]
	v_mfma_f32_16x16x32_bf16 v[44:47], v[88:91], v[124:127], v[44:47]
	s_waitcnt lgkmcnt(0)
	v_mfma_f32_16x16x32_bf16 v[48:51], v[92:95], v[112:115], v[48:51]
	v_mfma_f32_16x16x32_bf16 v[52:55], v[92:95], v[116:119], v[52:55]
	v_mfma_f32_16x16x32_bf16 v[56:59], v[92:95], v[120:123], v[56:59]
	v_mfma_f32_16x16x32_bf16 v[60:63], v[92:95], v[124:127], v[60:63]
	s_waitcnt vmcnt(0)
	s_barrier
	s_add_i32 s99, s99, 1
	s_cmp_eq_u32 s99, 16
	s_movk_i32 s0, 0x80
	s_cselect_b32 s0, 0xfffff880, s0
	s_cselect_b32 s99, 0, s99
	s_ashr_i32 s1, s0, 31
	s_add_u32 s26, s26, s0
	s_addc_u32 s27, s27, s1
	s_add_u32 s28, s28, s0
	s_addc_u32 s29, s29, s1
	s_mov_b32 m0, s5
	s_nop 0
	global_load_lds_dwordx4 v132, s[26:27] offset:0
	global_load_lds_dwordx4 v133, s[26:27] offset:1024
	global_load_lds_dwordx4 v134, s[26:27] offset:2048
	global_load_lds_dwordx4 v135, s[26:27] offset:3072
	s_mov_b32 m0, s6
	s_nop 0
	global_load_lds_dwordx4 v132, s[28:29] offset:0
	global_load_lds_dwordx4 v133, s[28:29] offset:1024
	global_load_lds_dwordx4 v134, s[28:29] offset:2048
	global_load_lds_dwordx4 v135, s[28:29] offset:3072
	ds_read_b128 v[64:67], v138 offset:0
	ds_read_b128 v[96:99], v142 offset:0
	ds_read_b128 v[100:103], v142 offset:2048
	ds_read_b128 v[104:107], v142 offset:4096
	ds_read_b128 v[108:111], v142 offset:6144
	ds_read_b128 v[68:71], v138 offset:2048
	ds_read_b128 v[72:75], v138 offset:4096
	ds_read_b128 v[76:79], v138 offset:6144
	s_waitcnt lgkmcnt(3)
	v_mfma_f32_16x16x32_bf16 v[0:3], v[64:67], v[96:99], v[0:3]
	v_mfma_f32_16x16x32_bf16 v[4:7], v[64:67], v[100:103], v[4:7]
	ds_read_b128 v[80:83], v139 offset:0
	v_mfma_f32_16x16x32_bf16 v[8:11], v[64:67], v[104:107], v[8:11]
	v_mfma_f32_16x16x32_bf16 v[12:15], v[64:67], v[108:111], v[12:15]
	ds_read_b128 v[112:115], v143 offset:0
	s_waitcnt lgkmcnt(4)
	v_mfma_f32_16x16x32_bf16 v[16:19], v[68:71], v[96:99], v[16:19]
	v_mfma_f32_16x16x32_bf16 v[20:23], v[68:71], v[100:103], v[20:23]
	ds_read_b128 v[116:119], v143 offset:2048
	v_mfma_f32_16x16x32_bf16 v[24:27], v[68:71], v[104:107], v[24:27]
	v_mfma_f32_16x16x32_bf16 v[28:31], v[68:71], v[108:111], v[28:31]
	ds_read_b128 v[120:123], v143 offset:4096
	s_waitcnt lgkmcnt(5)
	v_mfma_f32_16x16x32_bf16 v[32:35], v[72:75], v[96:99], v[32:35]
	v_mfma_f32_16x16x32_bf16 v[36:39], v[72:75], v[100:103], v[36:39]
	ds_read_b128 v[124:127], v143 offset:6144
	v_mfma_f32_16x16x32_bf16 v[40:43], v[72:75], v[104:107], v[40:43]
	v_mfma_f32_16x16x32_bf16 v[44:47], v[72:75], v[108:111], v[44:47]
	ds_read_b128 v[84:87], v139 offset:2048
	s_waitcnt lgkmcnt(6)
	v_mfma_f32_16x16x32_bf16 v[48:51], v[76:79], v[96:99], v[48:51]
	v_mfma_f32_16x16x32_bf16 v[52:55], v[76:79], v[100:103], v[52:55]
	ds_read_b128 v[88:91], v139 offset:4096
	v_mfma_f32_16x16x32_bf16 v[56:59], v[76:79], v[104:107], v[56:59]
	v_mfma_f32_16x16x32_bf16 v[60:63], v[76:79], v[108:111], v[60:63]
	ds_read_b128 v[92:95], v139 offset:6144
	s_waitcnt lgkmcnt(3)
	v_mfma_f32_16x16x32_bf16 v[0:3], v[80:83], v[112:115], v[0:3]
	v_mfma_f32_16x16x32_bf16 v[4:7], v[80:83], v[116:119], v[4:7]
	v_mfma_f32_16x16x32_bf16 v[8:11], v[80:83], v[120:123], v[8:11]
	v_mfma_f32_16x16x32_bf16 v[12:15], v[80:83], v[124:127], v[12:15]
	s_waitcnt lgkmcnt(2)
	v_mfma_f32_16x16x32_bf16 v[16:19], v[84:87], v[112:115], v[16:19]
	v_mfma_f32_16x16x32_bf16 v[20:23], v[84:87], v[116:119], v[20:23]
	v_mfma_f32_16x16x32_bf16 v[24:27], v[84:87], v[120:123], v[24:27]
	v_mfma_f32_16x16x32_bf16 v[28:31], v[84:87], v[124:127], v[28:31]
	s_waitcnt lgkmcnt(1)
	v_mfma_f32_16x16x32_bf16 v[32:35], v[88:91], v[112:115], v[32:35]
	v_mfma_f32_16x16x32_bf16 v[36:39], v[88:91], v[116:119], v[36:39]
	v_mfma_f32_16x16x32_bf16 v[40:43], v[88:91], v[120:123], v[40:43]
	v_mfma_f32_16x16x32_bf16 v[44:47], v[88:91], v[124:127], v[44:47]
	s_waitcnt lgkmcnt(0)
	v_mfma_f32_16x16x32_bf16 v[48:51], v[92:95], v[112:115], v[48:51]
	v_mfma_f32_16x16x32_bf16 v[52:55], v[92:95], v[116:119], v[52:55]
	v_mfma_f32_16x16x32_bf16 v[56:59], v[92:95], v[120:123], v[56:59]
	v_mfma_f32_16x16x32_bf16 v[60:63], v[92:95], v[124:127], v[60:63]
	s_waitcnt vmcnt(0)
	s_barrier
	s_add_i32 s99, s99, 1
	s_cmp_eq_u32 s99, 16
	s_movk_i32 s0, 0x80
	s_cselect_b32 s0, 0xfffff880, s0
	s_cselect_b32 s99, 0, s99
	s_ashr_i32 s1, s0, 31
	s_add_u32 s26, s26, s0
	s_addc_u32 s27, s27, s1
	s_add_u32 s28, s28, s0
	s_addc_u32 s29, s29, s1
	s_mov_b32 m0, s7
	s_nop 0
	global_load_lds_dwordx4 v132, s[26:27] offset:0
	global_load_lds_dwordx4 v133, s[26:27] offset:1024
	global_load_lds_dwordx4 v134, s[26:27] offset:2048
	global_load_lds_dwordx4 v135, s[26:27] offset:3072
	s_mov_b32 m0, s8
	s_nop 0
	global_load_lds_dwordx4 v132, s[28:29] offset:0
	global_load_lds_dwordx4 v133, s[28:29] offset:1024
	global_load_lds_dwordx4 v134, s[28:29] offset:2048
	global_load_lds_dwordx4 v135, s[28:29] offset:3072
	ds_read_b128 v[64:67], v136 offset:0
	ds_read_b128 v[96:99], v140 offset:0
	ds_read_b128 v[100:103], v140 offset:2048
	ds_read_b128 v[104:107], v140 offset:4096
	ds_read_b128 v[108:111], v140 offset:6144
	ds_read_b128 v[68:71], v136 offset:2048
	ds_read_b128 v[72:75], v136 offset:4096
	ds_read_b128 v[76:79], v136 offset:6144
	s_waitcnt lgkmcnt(3)
	v_mfma_f32_16x16x32_bf16 v[0:3], v[64:67], v[96:99], v[0:3]
	v_mfma_f32_16x16x32_bf16 v[4:7], v[64:67], v[100:103], v[4:7]
	ds_read_b128 v[80:83], v137 offset:0
	v_mfma_f32_16x16x32_bf16 v[8:11], v[64:67], v[104:107], v[8:11]
	v_mfma_f32_16x16x32_bf16 v[12:15], v[64:67], v[108:111], v[12:15]
	ds_read_b128 v[112:115], v141 offset:0
	s_waitcnt lgkmcnt(4)
	v_mfma_f32_16x16x32_bf16 v[16:19], v[68:71], v[96:99], v[16:19]
	v_mfma_f32_16x16x32_bf16 v[20:23], v[68:71], v[100:103], v[20:23]
	ds_read_b128 v[116:119], v141 offset:2048
	v_mfma_f32_16x16x32_bf16 v[24:27], v[68:71], v[104:107], v[24:27]
	v_mfma_f32_16x16x32_bf16 v[28:31], v[68:71], v[108:111], v[28:31]
	ds_read_b128 v[120:123], v141 offset:4096
	s_waitcnt lgkmcnt(5)
	v_mfma_f32_16x16x32_bf16 v[32:35], v[72:75], v[96:99], v[32:35]
	v_mfma_f32_16x16x32_bf16 v[36:39], v[72:75], v[100:103], v[36:39]
	ds_read_b128 v[124:127], v141 offset:6144
	v_mfma_f32_16x16x32_bf16 v[40:43], v[72:75], v[104:107], v[40:43]
	v_mfma_f32_16x16x32_bf16 v[44:47], v[72:75], v[108:111], v[44:47]
	ds_read_b128 v[84:87], v137 offset:2048
	s_waitcnt lgkmcnt(6)
	v_mfma_f32_16x16x32_bf16 v[48:51], v[76:79], v[96:99], v[48:51]
	v_mfma_f32_16x16x32_bf16 v[52:55], v[76:79], v[100:103], v[52:55]
	ds_read_b128 v[88:91], v137 offset:4096
	v_mfma_f32_16x16x32_bf16 v[56:59], v[76:79], v[104:107], v[56:59]
	v_mfma_f32_16x16x32_bf16 v[60:63], v[76:79], v[108:111], v[60:63]
	ds_read_b128 v[92:95], v137 offset:6144
	s_waitcnt lgkmcnt(3)
	v_mfma_f32_16x16x32_bf16 v[0:3], v[80:83], v[112:115], v[0:3]
	v_mfma_f32_16x16x32_bf16 v[4:7], v[80:83], v[116:119], v[4:7]
	v_mfma_f32_16x16x32_bf16 v[8:11], v[80:83], v[120:123], v[8:11]
	v_mfma_f32_16x16x32_bf16 v[12:15], v[80:83], v[124:127], v[12:15]
	s_waitcnt lgkmcnt(2)
	v_mfma_f32_16x16x32_bf16 v[16:19], v[84:87], v[112:115], v[16:19]
	v_mfma_f32_16x16x32_bf16 v[20:23], v[84:87], v[116:119], v[20:23]
	v_mfma_f32_16x16x32_bf16 v[24:27], v[84:87], v[120:123], v[24:27]
	v_mfma_f32_16x16x32_bf16 v[28:31], v[84:87], v[124:127], v[28:31]
	s_waitcnt lgkmcnt(1)
	v_mfma_f32_16x16x32_bf16 v[32:35], v[88:91], v[112:115], v[32:35]
	v_mfma_f32_16x16x32_bf16 v[36:39], v[88:91], v[116:119], v[36:39]
	v_mfma_f32_16x16x32_bf16 v[40:43], v[88:91], v[120:123], v[40:43]
	v_mfma_f32_16x16x32_bf16 v[44:47], v[88:91], v[124:127], v[44:47]
	s_waitcnt lgkmcnt(0)
	v_mfma_f32_16x16x32_bf16 v[48:51], v[92:95], v[112:115], v[48:51]
	v_mfma_f32_16x16x32_bf16 v[52:55], v[92:95], v[116:119], v[52:55]
	v_mfma_f32_16x16x32_bf16 v[56:59], v[92:95], v[120:123], v[56:59]
	v_mfma_f32_16x16x32_bf16 v[60:63], v[92:95], v[124:127], v[60:63]
	s_waitcnt vmcnt(0)
	s_barrier
	ds_read_b128 v[64:67], v138 offset:0
	ds_read_b128 v[96:99], v142 offset:0
	ds_read_b128 v[100:103], v142 offset:2048
	ds_read_b128 v[104:107], v142 offset:4096
	ds_read_b128 v[108:111], v142 offset:6144
	ds_read_b128 v[68:71], v138 offset:2048
	ds_read_b128 v[72:75], v138 offset:4096
	ds_read_b128 v[76:79], v138 offset:6144
	s_waitcnt lgkmcnt(3)
	v_mfma_f32_16x16x32_bf16 v[0:3], v[64:67], v[96:99], v[0:3]
	v_mfma_f32_16x16x32_bf16 v[4:7], v[64:67], v[100:103], v[4:7]
	ds_read_b128 v[80:83], v139 offset:0
	v_mfma_f32_16x16x32_bf16 v[8:11], v[64:67], v[104:107], v[8:11]
	v_mfma_f32_16x16x32_bf16 v[12:15], v[64:67], v[108:111], v[12:15]
	ds_read_b128 v[112:115], v143 offset:0
	s_waitcnt lgkmcnt(4)
	v_mfma_f32_16x16x32_bf16 v[16:19], v[68:71], v[96:99], v[16:19]
	v_mfma_f32_16x16x32_bf16 v[20:23], v[68:71], v[100:103], v[20:23]
	ds_read_b128 v[116:119], v143 offset:2048
	v_mfma_f32_16x16x32_bf16 v[24:27], v[68:71], v[104:107], v[24:27]
	v_mfma_f32_16x16x32_bf16 v[28:31], v[68:71], v[108:111], v[28:31]
	ds_read_b128 v[120:123], v143 offset:4096
	s_waitcnt lgkmcnt(5)
	v_mfma_f32_16x16x32_bf16 v[32:35], v[72:75], v[96:99], v[32:35]
	v_mfma_f32_16x16x32_bf16 v[36:39], v[72:75], v[100:103], v[36:39]
	ds_read_b128 v[124:127], v143 offset:6144
	v_mfma_f32_16x16x32_bf16 v[40:43], v[72:75], v[104:107], v[40:43]
	v_mfma_f32_16x16x32_bf16 v[44:47], v[72:75], v[108:111], v[44:47]
	ds_read_b128 v[84:87], v139 offset:2048
	s_waitcnt lgkmcnt(6)
	v_mfma_f32_16x16x32_bf16 v[48:51], v[76:79], v[96:99], v[48:51]
	v_mfma_f32_16x16x32_bf16 v[52:55], v[76:79], v[100:103], v[52:55]
	ds_read_b128 v[88:91], v139 offset:4096
	v_mfma_f32_16x16x32_bf16 v[56:59], v[76:79], v[104:107], v[56:59]
	v_mfma_f32_16x16x32_bf16 v[60:63], v[76:79], v[108:111], v[60:63]
	ds_read_b128 v[92:95], v139 offset:6144
	s_waitcnt lgkmcnt(3)
	v_mfma_f32_16x16x32_bf16 v[0:3], v[80:83], v[112:115], v[0:3]
	v_mfma_f32_16x16x32_bf16 v[4:7], v[80:83], v[116:119], v[4:7]
	v_mfma_f32_16x16x32_bf16 v[8:11], v[80:83], v[120:123], v[8:11]
	v_mfma_f32_16x16x32_bf16 v[12:15], v[80:83], v[124:127], v[12:15]
	s_waitcnt lgkmcnt(2)
	v_mfma_f32_16x16x32_bf16 v[16:19], v[84:87], v[112:115], v[16:19]
	v_mfma_f32_16x16x32_bf16 v[20:23], v[84:87], v[116:119], v[20:23]
	v_mfma_f32_16x16x32_bf16 v[24:27], v[84:87], v[120:123], v[24:27]
	v_mfma_f32_16x16x32_bf16 v[28:31], v[84:87], v[124:127], v[28:31]
	s_waitcnt lgkmcnt(1)
	v_mfma_f32_16x16x32_bf16 v[32:35], v[88:91], v[112:115], v[32:35]
	v_mfma_f32_16x16x32_bf16 v[36:39], v[88:91], v[116:119], v[36:39]
	v_mfma_f32_16x16x32_bf16 v[40:43], v[88:91], v[120:123], v[40:43]
	v_mfma_f32_16x16x32_bf16 v[44:47], v[88:91], v[124:127], v[44:47]
	s_waitcnt lgkmcnt(0)
	v_mfma_f32_16x16x32_bf16 v[48:51], v[92:95], v[112:115], v[48:51]
	v_mfma_f32_16x16x32_bf16 v[52:55], v[92:95], v[116:119], v[52:55]
	v_mfma_f32_16x16x32_bf16 v[56:59], v[92:95], v[120:123], v[56:59]
	v_mfma_f32_16x16x32_bf16 v[60:63], v[92:95], v[124:127], v[60:63]
	s_add_i32 s100, s100, 1
	s_cmp_lt_u32 s100, 9
	s_cbranch_scc0 .Lgin_r9
	s_and_b32 s0, s101, 7
	s_add_i32 s0, s0, s100
	s_cmp_ge_u32 s0, 9
	s_cbranch_scc0 .Lgin_rk
	s_sub_u32 s0, s0, 9

.Lgin_nonext:
	s_and_b32 s0, s25, 63
	s_lshr_b32 s1, s25, 6
	s_mul_i32 s4, s0, 0x250000
	s_lshl_b32 s39, s1, 8
	s_add_u32 s4, s4, s39
	s_add_u32 s4, s4, 0x92a6100
	s_add_u32 s36, s96, s4
	s_addc_u32 s37, s97, 0
	s_nop 7
	v_cvt_pk_bf16_f32 v0, v0, v1
	v_cvt_pk_bf16_f32 v1, v2, v3
	v_cvt_pk_bf16_f32 v2, v16, v17
	v_cvt_pk_bf16_f32 v3, v18, v19
	s_nop 1
	v_permlane16_swap_b32 v0, v2
	v_permlane16_swap_b32 v1, v3
	s_nop 1
	global_store_dwordx4 v146, v[0:3], s[36:37] offset:0
	v_cvt_pk_bf16_f32 v32, v32, v33
	v_cvt_pk_bf16_f32 v33, v34, v35
	v_cvt_pk_bf16_f32 v34, v48, v49
	v_cvt_pk_bf16_f32 v35, v50, v51
	s_nop 1
	v_permlane16_swap_b32 v32, v34
	v_permlane16_swap_b32 v33, v35
	s_nop 1
	global_store_dwordx4 v146, v[32:35], s[36:37] offset:64
	v_cvt_pk_bf16_f32 v4, v4, v5
	v_cvt_pk_bf16_f32 v5, v6, v7
	v_cvt_pk_bf16_f32 v6, v20, v21
	v_cvt_pk_bf16_f32 v7, v22, v23
	s_nop 1
	v_permlane16_swap_b32 v4, v6
	v_permlane16_swap_b32 v5, v7
	s_nop 1
	global_store_dwordx4 v147, v[4:7], s[36:37] offset:0
	v_cvt_pk_bf16_f32 v36, v36, v37
	v_cvt_pk_bf16_f32 v37, v38, v39
	v_cvt_pk_bf16_f32 v38, v52, v53
	v_cvt_pk_bf16_f32 v39, v54, v55
	s_nop 1
	v_permlane16_swap_b32 v36, v38
	v_permlane16_swap_b32 v37, v39
	s_nop 1
	global_store_dwordx4 v147, v[36:39], s[36:37] offset:64
	v_cvt_pk_bf16_f32 v8, v8, v9
	v_cvt_pk_bf16_f32 v9, v10, v11
	v_cvt_pk_bf16_f32 v10, v24, v25
	v_cvt_pk_bf16_f32 v11, v26, v27
	s_nop 1
	v_permlane16_swap_b32 v8, v10
	v_permlane16_swap_b32 v9, v11
	s_nop 1
	global_store_dwordx4 v148, v[8:11], s[36:37] offset:0
	v_cvt_pk_bf16_f32 v40, v40, v41
	v_cvt_pk_bf16_f32 v41, v42, v43
	v_cvt_pk_bf16_f32 v42, v56, v57
	v_cvt_pk_bf16_f32 v43, v58, v59
	s_nop 1
	v_permlane16_swap_b32 v40, v42
	v_permlane16_swap_b32 v41, v43
	s_nop 1
	global_store_dwordx4 v148, v[40:43], s[36:37] offset:64
	v_cvt_pk_bf16_f32 v12, v12, v13
	v_cvt_pk_bf16_f32 v13, v14, v15
	v_cvt_pk_bf16_f32 v14, v28, v29
	v_cvt_pk_bf16_f32 v15, v30, v31
	s_nop 1
	v_permlane16_swap_b32 v12, v14
	v_permlane16_swap_b32 v13, v15
	s_nop 1
	global_store_dwordx4 v149, v[12:15], s[36:37] offset:0
	v_cvt_pk_bf16_f32 v44, v44, v45
	v_cvt_pk_bf16_f32 v45, v46, v47
	v_cvt_pk_bf16_f32 v46, v60, v61
	v_cvt_pk_bf16_f32 v47, v62, v63
	s_nop 1
	v_permlane16_swap_b32 v44, v46
	v_permlane16_swap_b32 v45, v47
	s_nop 1
	global_store_dwordx4 v149, v[44:47], s[36:37] offset:64
	s_mov_b32 s25, s38
	s_cmpk_lt_u32 s25, 0x1280
	s_cbranch_scc1 .Lgin_tile
	v_readlane_b32 s36, v255, 33
	v_readlane_b32 s37, v255, 34
	v_readlane_b32 s38, v255, 35
	v_readlane_b32 s39, v255, 36
